# GELU epilogue: |v| folded into v_fma source modifier (2 v_and + v_pk_fma -> 2 v_fma per pair), on top of the max/fma select
# speedup vs baseline: 1.0104x; 1.0017x over previous
; #define LAS __attribute__((address_space(3)))
; __device__ __forceinline__ unsigned cvt_pk_bf16(float lo, float hi) { unsigned r; asm volatile("v_cvt_pk_bf16_f32 %0, %1, %2" : "=v"(r) : "v"(lo), "v"(hi)); return r; }
; __device__ __forceinline__ f32x2 gelu_pk(f32x2 v) {
;     const f32x2 av = __builtin_elementwise_abs(v), d = av * 0.2316418882f + 1.0f;
;     f32x2 t; t.x = __builtin_amdgcn_rcpf(d.x); t.y = __builtin_amdgcn_rcpf(d.y);
;     f32x2 q = t * 0.5307027145f + (-0.7265760135f); q = q * t + 0.7107068705f; q = q * t + (-0.142248368f); q = q * t + 0.127414796f; q = q * t;
;     const f32x2 s = (v * v) * (-0.72134752044f);
;     f32x2 e; e.x = __builtin_amdgcn_exp2f(s.x); e.y = __builtin_amdgcn_exp2f(s.y);
;     const f32x2 m = v * (q * e), r = v - m;
;     f32x2 o; o.x = v.x < 0.f ? m.x : r.x; o.y = v.y < 0.f ? m.y : r.y; return o;
; }
;     __device__ __forceinline__ void operator()(const f32x4 (&acc)[2][2][4][2], const Unit& u, int wr, int wc, int fr, int fq) const {
;         const int row0 = u.pm * BM + wr * 64 + fr, col0 = u.pn * BM + wc * 32 + 8 * fq; const bool isv = u.pn >= 4;
;         LAS float* part = (LAS float*)(lds + PART_OFF);
;         float rsv[2][4]; rstd8(ss, row0, rsv);
; #pragma unroll
;         for (int ai = 0; ai < 2; ++ai)
; #pragma unroll
;             for (int m = 0; m < 4; ++m) { const int row = row0 + ai * HALF + m * 16; const float rs = rsv[ai][m]; bf16_t* rowp = O + (size_t)row * ldc + col0; float s1 = 0.f, s2 = 0.f;
; #pragma unroll
;                 for (int bj = 0; bj < 2; ++bj) { f32x4 v0 = acc[ai][bj][m][0] * rs, v1 = acc[ai][bj][m][1] * rs;
;                     const f32x2 a = gelu_pk((f32x2){v0[0], v0[1]}), b = gelu_pk((f32x2){v0[2], v0[3]}), c = gelu_pk((f32x2){v1[0], v1[1]}), d = gelu_pk((f32x2){v1[2], v1[3]});
;                     s1 += ((a.x + a.y) + (b.x + b.y)) + ((c.x + c.y) + (d.x + d.y));
;                     s2 += ((a.x * a.x + a.y * a.y) + (b.x * b.x + b.y * b.y)) + ((c.x * c.x + c.y * c.y) + (d.x * d.x + d.y * d.y));
;                     u32x4 w; w.x = cvt_pk_bf16(a.x, a.y); w.y = cvt_pk_bf16(b.x, b.y); w.z = cvt_pk_bf16(c.x, c.y); w.w = cvt_pk_bf16(d.x, d.y);
;                     *(u32x4*)(rowp + bj * HALF) = w; }
.LBB0_352:
	s_lshl_b32 s27, s10, 8
	v_add_u32_e32 v190, s27, v184
	v_ashrrev_i32_e32 v191, 31, v190
	v_lshl_add_u64 v[34:35], v[190:191], 4, s[22:23]
	global_load_dwordx4 v[176:179], v[34:35], off
	v_or_b32_e32 v174, 16, v190
	v_or_b32_e32 v172, 32, v190
	v_or_b32_e32 v170, 48, v190
	v_add_u32_e32 v168, 0x80, v190
	v_add_u32_e32 v166, 0x90, v190
	v_add_u32_e32 v164, 0xa0, v190
	v_add_u32_e32 v162, 0xb0, v190
	s_mov_b32 s4, 0xbf3a00e3
	v_ashrrev_i32_e32 v175, 31, v174
	v_lshl_add_u64 v[34:35], v[174:175], 4, s[22:23]
	v_ashrrev_i32_e32 v173, 31, v172
	global_load_dwordx4 v[146:149], v[34:35], off
	v_lshl_add_u64 v[34:35], v[172:173], 4, s[22:23]
	v_ashrrev_i32_e32 v171, 31, v170
	global_load_dwordx4 v[126:129], v[34:35], off
	v_lshl_add_u64 v[34:35], v[170:171], 4, s[22:23]
	v_ashrrev_i32_e32 v169, 31, v168
	global_load_dwordx4 v[110:113], v[34:35], off
	v_lshl_add_u64 v[34:35], v[168:169], 4, s[22:23]
	v_ashrrev_i32_e32 v167, 31, v166
	global_load_dwordx4 v[94:97], v[34:35], off
	v_lshl_add_u64 v[34:35], v[166:167], 4, s[22:23]
	v_ashrrev_i32_e32 v165, 31, v164
	global_load_dwordx4 v[74:77], v[34:35], off
	v_lshl_add_u64 v[34:35], v[164:165], 4, s[22:23]
	v_ashrrev_i32_e32 v163, 31, v162
	global_load_dwordx4 v[54:57], v[34:35], off
	v_lshl_add_u64 v[34:35], v[162:163], 4, s[22:23]
	global_load_dwordx4 v[34:37], v[34:35], off
	v_lshl_or_b32 v160, s46, 8, v185
	v_ashrrev_i32_e32 v161, 31, v160
	s_cmp_gt_i32 s46, 3
	s_cselect_b64 s[36:37], -1, 0
	s_cmp_lt_i32 s46, 4
	s_waitcnt vmcnt(0) lgkmcnt(0)
	v_mov_b32_e32 v192, v177
	v_mov_b32_e32 v193, v178
	v_mov_b32_e32 v177, v179
	v_pk_add_f32 v[176:177], v[192:193], v[176:177]
	s_nop 0
	v_add_f32_e32 v0, v176, v177
	v_fmamk_f32 v0, v0, 0x3a800000, v224
	v_rsq_f32_e32 v0, v0
	v_lshlrev_b64 v[176:177], 12, v[190:191]
	v_lshl_add_u64 v[176:177], s[20:21], 0, v[176:177]
	v_lshl_add_u64 v[176:177], v[160:161], 1, v[176:177]
	v_pk_mul_f32 v[178:179], v[154:155], v[0:1] op_sel_hi:[1,0]
	v_pk_mul_f32 v[154:155], v[150:151], v[0:1] op_sel_hi:[1,0]
	s_nop 0
	s_nop 0
	v_fma_f32 v150, |v178|, s64, 1.0
	v_fma_f32 v151, |v179|, s64, 1.0
	v_pk_mul_f32 v[202:203], v[178:179], v[178:179]
	v_rcp_f32_e32 v190, v150
	v_rcp_f32_e32 v191, v151
	v_mov_b64_e32 v[150:151], s[4:5]
	v_pk_mul_f32 v[202:203], v[202:203], s[76:77] op_sel_hi:[1,0]
	s_nop 0
	v_pk_fma_f32 v[192:193], v[190:191], s[66:67], v[150:151] op_sel_hi:[1,0,0]
	v_exp_f32_e32 v202, v202
	v_pk_fma_f32 v[192:193], v[190:191], v[192:193], s[70:71] op_sel_hi:[1,1,0]
	v_exp_f32_e32 v203, v203
	v_pk_fma_f32 v[192:193], v[190:191], v[192:193], s[72:73] op_sel_hi:[1,1,0]
	v_pk_mul_f32 v[156:157], v[156:157], v[0:1] op_sel_hi:[1,0]
	v_pk_fma_f32 v[192:193], v[190:191], v[192:193], s[74:75] op_sel_hi:[1,1,0]
	v_pk_mul_f32 v[152:153], v[152:153], v[0:1] op_sel_hi:[1,0]
	v_pk_mul_f32 v[190:191], v[190:191], v[192:193]
	v_pk_mul_f32 v[192:193], v[156:157], v[156:157]
	v_pk_mul_f32 v[190:191], v[202:203], v[190:191]
	v_pk_mul_f32 v[192:193], v[192:193], s[76:77] op_sel_hi:[1,0]
	v_max_f32_e32 v202, 0, v178
	v_max_f32_e32 v203, 0, v179
	v_fma_f32 v178, -|v178|, v190, v202
	v_fma_f32 v179, -|v179|, v191, v203
	v_exp_f32_e32 v192, v192
	s_nop 0
	s_nop 0
	s_nop 0
	v_exp_f32_e32 v193, v193
	s_nop 0
	s_nop 0
	v_fma_f32 v190, |v156|, s64, 1.0
	v_fma_f32 v191, |v157|, s64, 1.0
	s_nop 0
	v_rcp_f32_e32 v190, v190
	v_rcp_f32_e32 v191, v191
	v_pk_mul_f32 v[142:143], v[142:143], v[0:1] op_sel_hi:[1,0]
	v_pk_mul_f32 v[144:145], v[144:145], v[0:1] op_sel_hi:[1,0]
	v_pk_mul_f32 v[140:141], v[140:141], v[0:1] op_sel_hi:[1,0]
	v_pk_fma_f32 v[202:203], v[190:191], s[66:67], v[150:151] op_sel_hi:[1,0,0]
	s_nop 0
	v_pk_fma_f32 v[202:203], v[190:191], v[202:203], s[70:71] op_sel_hi:[1,1,0]
	s_nop 0
	v_pk_fma_f32 v[202:203], v[190:191], v[202:203], s[72:73] op_sel_hi:[1,1,0]
	s_nop 0
	v_pk_fma_f32 v[202:203], v[190:191], v[202:203], s[74:75] op_sel_hi:[1,1,0]
	s_nop 0
	v_pk_mul_f32 v[190:191], v[190:191], v[202:203]
	v_pk_mul_f32 v[202:203], v[154:155], v[154:155]
	v_pk_mul_f32 v[190:191], v[192:193], v[190:191]
	v_pk_mul_f32 v[202:203], v[202:203], s[76:77] op_sel_hi:[1,0]
	v_max_f32_e32 v192, 0, v156
	v_max_f32_e32 v193, 0, v157
	v_fma_f32 v189, -|v156|, v190, v192
	v_fma_f32 v190, -|v157|, v191, v193
	s_nop 0
	s_nop 0
	s_nop 0
	s_nop 0
	v_fma_f32 v156, |v154|, s64, 1.0
	v_fma_f32 v157, |v155|, s64, 1.0
	s_nop 0
	v_rcp_f32_e32 v156, v156
	v_rcp_f32_e32 v157, v157
	v_exp_f32_e32 v202, v202
	v_exp_f32_e32 v203, v203
	s_nop 0
	v_pk_fma_f32 v[192:193], v[156:157], s[66:67], v[150:151] op_sel_hi:[1,0,0]
	s_nop 0
	v_pk_fma_f32 v[192:193], v[156:157], v[192:193], s[70:71] op_sel_hi:[1,1,0]
	s_nop 0
	v_pk_fma_f32 v[192:193], v[156:157], v[192:193], s[72:73] op_sel_hi:[1,1,0]
	s_nop 0
	v_pk_fma_f32 v[192:193], v[156:157], v[192:193], s[74:75] op_sel_hi:[1,1,0]
	s_nop 0
	v_pk_mul_f32 v[192:193], v[156:157], v[192:193]
	v_pk_mul_f32 v[156:157], v[152:153], v[152:153]
	v_pk_mul_f32 v[192:193], v[202:203], v[192:193]
	v_pk_mul_f32 v[156:157], v[156:157], s[76:77] op_sel_hi:[1,0]
	v_max_f32_e32 v202, 0, v154
	v_max_f32_e32 v203, 0, v155
	v_fma_f32 v154, -|v154|, v192, v202
	v_fma_f32 v155, -|v155|, v193, v203
	v_exp_f32_e32 v156, v156
	s_nop 0
	s_nop 0
	s_nop 0
	v_exp_f32_e32 v157, v157
	s_nop 0
	s_nop 0
	v_fma_f32 v192, |v152|, s64, 1.0
	v_fma_f32 v193, |v153|, s64, 1.0
	s_nop 0
	v_rcp_f32_e32 v192, v192
	v_rcp_f32_e32 v193, v193
	s_nop 0
	v_pk_fma_f32 v[202:203], v[192:193], s[66:67], v[150:151] op_sel_hi:[1,0,0]
	s_nop 0
	v_pk_fma_f32 v[202:203], v[192:193], v[202:203], s[70:71] op_sel_hi:[1,1,0]
	s_nop 0
	v_pk_fma_f32 v[202:203], v[192:193], v[202:203], s[72:73] op_sel_hi:[1,1,0]
	s_nop 0
; __device__ __forceinline__ unsigned cvt_pk_bf16(float lo, float hi) { unsigned r; asm volatile("v_cvt_pk_bf16_f32 %0, %1, %2" : "=v"(r) : "v"(lo), "v"(hi)); return r; }
; __device__ __forceinline__ f32x2 gelu_pk(f32x2 v) {
;     const f32x2 av = __builtin_elementwise_abs(v), d = av * 0.2316418882f + 1.0f;
;     f32x2 t; t.x = __builtin_amdgcn_rcpf(d.x); t.y = __builtin_amdgcn_rcpf(d.y);
;     f32x2 q = t * 0.5307027145f + (-0.7265760135f); q = q * t + 0.7107068705f; q = q * t + (-0.142248368f); q = q * t + 0.127414796f; q = q * t;
;     const f32x2 s = (v * v) * (-0.72134752044f);
;     f32x2 e; e.x = __builtin_amdgcn_exp2f(s.x); e.y = __builtin_amdgcn_exp2f(s.y);
;     const f32x2 m = v * (q * e), r = v - m;
;     f32x2 o; o.x = v.x < 0.f ? m.x : r.x; o.y = v.y < 0.f ? m.y : r.y; return o;
; }
;     __device__ __forceinline__ void operator()(const f32x4 (&acc)[2][2][4][2], const Unit& u, int wr, int wc, int fr, int fq) const {
;     ...
;             for (int m = 0; m < 4; ++m) { const int row = row0 + ai * HALF + m * 16; const float rs = rsv[ai][m]; bf16_t* rowp = O + (size_t)row * ldc + col0; float s1 = 0.f, s2 = 0.f;
; #pragma unroll
;                 for (int bj = 0; bj < 2; ++bj) { f32x4 v0 = acc[ai][bj][m][0] * rs, v1 = acc[ai][bj][m][1] * rs;
;                     const f32x2 a = gelu_pk((f32x2){v0[0], v0[1]}), b = gelu_pk((f32x2){v0[2], v0[3]}), c = gelu_pk((f32x2){v1[0], v1[1]}), d = gelu_pk((f32x2){v1[2], v1[3]});
;                     s1 += ((a.x + a.y) + (b.x + b.y)) + ((c.x + c.y) + (d.x + d.y));
;                     s2 += ((a.x * a.x + a.y * a.y) + (b.x * b.x + b.y * b.y)) + ((c.x * c.x + c.y * c.y) + (d.x * d.x + d.y * d.y));
;                     u32x4 w; w.x = cvt_pk_bf16(a.x, a.y); w.y = cvt_pk_bf16(b.x, b.y); w.z = cvt_pk_bf16(c.x, c.y); w.w = cvt_pk_bf16(d.x, d.y);
;                     *(u32x4*)(rowp + bj * HALF) = w; }
;                 if (isv) { s1 += __shfl_xor(s1, 16); s1 += __shfl_xor(s1, 32); s2 += __shfl_xor(s2, 16); s2 += __shfl_xor(s2, 32);
;                     if (fq == 0) { const int rl = ai * HALF + wr * 64 + m * 16 + fr; part[rl * 4 + wc] = s1; part[1024 + rl * 4 + wc] = s2; } } }
	v_pk_fma_f32 v[202:203], v[192:193], v[202:203], s[74:75] op_sel_hi:[1,1,0]
	s_nop 0
	v_pk_mul_f32 v[192:193], v[192:193], v[202:203]
	v_cvt_pk_bf16_f32 v202, v178, v179
	v_cvt_pk_bf16_f32 v203, v189, v190
	v_cvt_pk_bf16_f32 v204, v154, v155
	s_nop 0
	v_pk_mul_f32 v[156:157], v[156:157], v[192:193]
	s_nop 0
	v_max_f32_e32 v192, 0, v152
	v_max_f32_e32 v193, 0, v153
	v_fma_f32 v152, -|v152|, v156, v192
	v_fma_f32 v153, -|v153|, v157, v193
	s_nop 0
	s_nop 0
	s_nop 0
	s_nop 1
	s_nop 0
	v_pk_mul_f32 v[156:157], v[138:139], v[0:1] op_sel_hi:[1,0]
	s_nop 0
	s_nop 0
	v_fma_f32 v138, |v142|, s64, 1.0
	v_fma_f32 v139, |v143|, s64, 1.0
	v_cvt_pk_bf16_f32 v205, v152, v153
	global_store_dwordx4 v[176:177], v[202:205], off
	v_rcp_f32_e32 v138, v138
	v_rcp_f32_e32 v139, v139
	v_pk_mul_f32 v[202:203], v[142:143], v[142:143]
	s_nop 0
	v_pk_mul_f32 v[202:203], v[202:203], s[76:77] op_sel_hi:[1,0]
	v_pk_fma_f32 v[192:193], v[138:139], s[66:67], v[150:151] op_sel_hi:[1,0,0]
	v_exp_f32_e32 v202, v202
	v_pk_fma_f32 v[192:193], v[138:139], v[192:193], s[70:71] op_sel_hi:[1,1,0]
	v_exp_f32_e32 v203, v203
	v_pk_fma_f32 v[192:193], v[138:139], v[192:193], s[72:73] op_sel_hi:[1,1,0]
	s_nop 0
	v_pk_fma_f32 v[192:193], v[138:139], v[192:193], s[74:75] op_sel_hi:[1,1,0]
	s_nop 0
	v_pk_mul_f32 v[138:139], v[138:139], v[192:193]
	v_pk_mul_f32 v[192:193], v[144:145], v[144:145]
	v_pk_mul_f32 v[138:139], v[202:203], v[138:139]
	v_pk_mul_f32 v[192:193], v[192:193], s[76:77] op_sel_hi:[1,0]
	v_max_f32_e32 v202, 0, v142
	v_max_f32_e32 v203, 0, v143
	v_fma_f32 v0, -|v142|, v138, v202
	v_fma_f32 v138, -|v143|, v139, v203
	s_nop 0
	s_nop 0
	s_nop 0
	s_nop 0
	v_fma_f32 v142, |v144|, s64, 1.0
	v_fma_f32 v143, |v145|, s64, 1.0
	s_nop 0
	v_rcp_f32_e32 v142, v142
	v_rcp_f32_e32 v143, v143
	v_exp_f32_e32 v192, v192
	v_exp_f32_e32 v193, v193
	s_nop 0
	v_pk_fma_f32 v[202:203], v[142:143], s[66:67], v[150:151] op_sel_hi:[1,0,0]
	s_nop 0
	v_pk_fma_f32 v[202:203], v[142:143], v[202:203], s[70:71] op_sel_hi:[1,1,0]
	s_nop 0
	v_pk_fma_f32 v[202:203], v[142:143], v[202:203], s[72:73] op_sel_hi:[1,1,0]
	s_nop 0
	v_pk_fma_f32 v[202:203], v[142:143], v[202:203], s[74:75] op_sel_hi:[1,1,0]
	s_nop 0
	v_pk_mul_f32 v[142:143], v[142:143], v[202:203]
	v_pk_mul_f32 v[202:203], v[156:157], v[156:157]
	v_pk_mul_f32 v[142:143], v[192:193], v[142:143]
	v_pk_mul_f32 v[202:203], v[202:203], s[76:77] op_sel_hi:[1,0]
	v_max_f32_e32 v192, 0, v144
	v_max_f32_e32 v193, 0, v145
	v_fma_f32 v139, -|v144|, v142, v192
	v_fma_f32 v142, -|v145|, v143, v193
	s_nop 0
	s_nop 0
	s_nop 0
	s_nop 0
	v_fma_f32 v144, |v156|, s64, 1.0
	v_fma_f32 v145, |v157|, s64, 1.0
	s_nop 0
	v_rcp_f32_e32 v144, v144
	v_rcp_f32_e32 v145, v145
	v_exp_f32_e32 v202, v202
	v_exp_f32_e32 v203, v203
	s_nop 0
	v_pk_fma_f32 v[192:193], v[144:145], s[66:67], v[150:151] op_sel_hi:[1,0,0]
	s_nop 0
	v_pk_fma_f32 v[192:193], v[144:145], v[192:193], s[70:71] op_sel_hi:[1,1,0]
	s_nop 0
	v_pk_fma_f32 v[192:193], v[144:145], v[192:193], s[72:73] op_sel_hi:[1,1,0]
	s_nop 0
	v_pk_fma_f32 v[192:193], v[144:145], v[192:193], s[74:75] op_sel_hi:[1,1,0]
	s_nop 0
	v_pk_mul_f32 v[144:145], v[144:145], v[192:193]
	v_pk_mul_f32 v[192:193], v[140:141], v[140:141]
	v_pk_mul_f32 v[144:145], v[202:203], v[144:145]
	s_nop 0
	v_max_f32_e32 v202, 0, v156
	v_max_f32_e32 v203, 0, v157
	v_fma_f32 v143, -|v156|, v144, v202
	v_fma_f32 v144, -|v157|, v145, v203
	s_nop 0
	s_nop 0
	s_nop 0
	s_nop 0
	v_fma_f32 v156, |v140|, s64, 1.0
	v_fma_f32 v157, |v141|, s64, 1.0
	s_nop 0
	v_rcp_f32_e32 v156, v156
	v_rcp_f32_e32 v157, v157
	s_nop 0
	v_cvt_pk_bf16_f32 v202, v0, v138
	v_cvt_pk_bf16_f32 v203, v139, v142
	v_pk_fma_f32 v[150:151], v[156:157], s[66:67], v[150:151] op_sel_hi:[1,0,0]
	v_cvt_pk_bf16_f32 v204, v143, v144
	s_nop 0
	v_pk_fma_f32 v[150:151], v[156:157], v[150:151], s[70:71] op_sel_hi:[1,1,0]
	s_nop 0
	v_pk_fma_f32 v[150:151], v[156:157], v[150:151], s[72:73] op_sel_hi:[1,1,0]
	s_nop 0
	v_pk_fma_f32 v[150:151], v[156:157], v[150:151], s[74:75] op_sel_hi:[1,1,0]
	s_nop 0
	v_pk_mul_f32 v[150:151], v[156:157], v[150:151]
	v_pk_mul_f32 v[156:157], v[192:193], s[76:77] op_sel_hi:[1,0]
	s_nop 0
	v_exp_f32_e32 v156, v156
	v_exp_f32_e32 v157, v157
	s_nop 0
	v_pk_mul_f32 v[150:151], v[156:157], v[150:151]
	s_nop 0
	v_max_f32_e32 v156, 0, v140
	v_max_f32_e32 v157, 0, v141
	v_fma_f32 v140, -|v140|, v150, v156
	v_fma_f32 v141, -|v141|, v151, v157
	s_nop 0
	s_nop 0
	s_nop 0
	s_nop 1
	s_nop 0
	v_cvt_pk_bf16_f32 v205, v140, v141
	global_store_dwordx4 v[176:177], v[202:205], off offset:256
	s_cbranch_scc1 .LBB0_356
	v_mul_f32_e32 v145, v179, v179
	v_mul_f32_e32 v150, v190, v190
	v_fmac_f32_e32 v145, v178, v178
	v_fmac_f32_e32 v150, v189, v189
	v_add_f32_e32 v145, v145, v150
	v_mul_f32_e32 v150, v155, v155
	v_mul_f32_e32 v151, v153, v153
	v_fmac_f32_e32 v150, v154, v154
	v_fmac_f32_e32 v151, v152, v152
	v_add_f32_e32 v150, v150, v151
	v_add_f32_e32 v145, v145, v150
	v_mul_f32_e32 v150, v138, v138
	v_fmac_f32_e32 v150, v0, v0
	v_mul_f32_e32 v151, v142, v142
	v_add_f32_e32 v0, v0, v138
	v_add_f32_e32 v138, v139, v142
	v_fmac_f32_e32 v151, v139, v139
	v_add_f32_e32 v0, v0, v138
	v_add_f32_e32 v138, v143, v144
	v_add_f32_e32 v139, v140, v141
	v_add_f32_e32 v157, v178, v179
	v_add_f32_e32 v176, v189, v190
	v_add_f32_e32 v154, v154, v155
	v_add_f32_e32 v152, v152, v153
	v_add_f32_e32 v138, v138, v139
	v_and_b32_e32 v139, 64, v226
	v_add_f32_e32 v157, v157, v176
	v_add_f32_e32 v152, v154, v152
	v_add_f32_e32 v0, v0, v138
	v_xor_b32_e32 v138, 16, v226
	v_add_u32_e32 v139, 64, v139
	v_add_f32_e32 v152, v157, v152
	v_cmp_lt_i32_e32 vcc, v138, v139
	v_add_f32_e32 v150, v150, v151
	v_mul_f32_e32 v151, v144, v144
	v_mul_f32_e32 v156, v141, v141
	v_add_f32_e32 v152, 0, v152
	v_cndmask_b32_e32 v138, v226, v138, vcc
	v_fmac_f32_e32 v151, v143, v143
	v_add_f32_e32 v0, v0, v152
	v_lshlrev_b32_e32 v138, 2, v138
	v_fmac_f32_e32 v156, v140, v140
	v_mov_b32_e32 v141, v0
	s_nop 1
	v_permlane16_swap_b32_e32 v141, v0
	v_add_f32_e32 v140, v151, v156
	v_add_f32_e32 v140, v150, v140
	v_add_f32_e32 v140, v145, v140
	v_mov_b32_e32 v142, v140
	s_nop 1
	v_permlane16_swap_b32_e32 v142, v140
	s_waitcnt lgkmcnt(0)
	v_add_f32_e32 v0, v0, v141
	v_xor_b32_e32 v141, 32, v226
	v_cmp_lt_i32_e32 vcc, v141, v139
	v_add_f32_e32 v139, v140, v142
	s_nop 0
	v_cndmask_b32_e32 v138, v226, v141, vcc
	v_lshlrev_b32_e32 v141, 2, v138
	v_mov_b32_e32 v138, v0
	s_nop 1
	v_permlane32_swap_b32_e32 v138, v0
	v_mov_b32_e32 v140, v139
	s_nop 1
	v_permlane32_swap_b32_e32 v140, v139
	s_and_saveexec_b64 s[4:5], s[6:7]
	s_cbranch_execz .LBB0_355
	s_waitcnt lgkmcnt(0)
	v_add_f32_e32 v139, v139, v140
	v_add_f32_e32 v0, v0, v138
	ds_write2st64_b32 v186, v0, v139 offset1:16

; __device__ __forceinline__ unsigned cvt_pk_bf16(float lo, float hi) { unsigned r; asm volatile("v_cvt_pk_bf16_f32 %0, %1, %2" : "=v"(r) : "v"(lo), "v"(hi)); return r; }
; __device__ __forceinline__ f32x2 gelu_pk(f32x2 v) {
;     const f32x2 av = __builtin_elementwise_abs(v), d = av * 0.2316418882f + 1.0f;
;     f32x2 t; t.x = __builtin_amdgcn_rcpf(d.x); t.y = __builtin_amdgcn_rcpf(d.y);
;     f32x2 q = t * 0.5307027145f + (-0.7265760135f); q = q * t + 0.7107068705f; q = q * t + (-0.142248368f); q = q * t + 0.127414796f; q = q * t;
;     const f32x2 s = (v * v) * (-0.72134752044f);
;     f32x2 e; e.x = __builtin_amdgcn_exp2f(s.x); e.y = __builtin_amdgcn_exp2f(s.y);
;     const f32x2 m = v * (q * e), r = v - m;
;     f32x2 o; o.x = v.x < 0.f ? m.x : r.x; o.y = v.y < 0.f ? m.y : r.y; return o;
; }
;     __device__ __forceinline__ void operator()(const f32x4 (&acc)[2][2][4][2], const Unit& u, int wr, int wc, int fr, int fq) const {
;     ...
;             for (int m = 0; m < 4; ++m) { const int row = row0 + ai * HALF + m * 16; const float rs = rsv[ai][m]; bf16_t* rowp = O + (size_t)row * ldc + col0; float s1 = 0.f, s2 = 0.f;
; #pragma unroll
;                 for (int bj = 0; bj < 2; ++bj) { f32x4 v0 = acc[ai][bj][m][0] * rs, v1 = acc[ai][bj][m][1] * rs;
;                     const f32x2 a = gelu_pk((f32x2){v0[0], v0[1]}), b = gelu_pk((f32x2){v0[2], v0[3]}), c = gelu_pk((f32x2){v1[0], v1[1]}), d = gelu_pk((f32x2){v1[2], v1[3]});
;                     s1 += ((a.x + a.y) + (b.x + b.y)) + ((c.x + c.y) + (d.x + d.y));
;                     s2 += ((a.x * a.x + a.y * a.y) + (b.x * b.x + b.y * b.y)) + ((c.x * c.x + c.y * c.y) + (d.x * d.x + d.y * d.y));
;                     u32x4 w; w.x = cvt_pk_bf16(a.x, a.y); w.y = cvt_pk_bf16(b.x, b.y); w.z = cvt_pk_bf16(c.x, c.y); w.w = cvt_pk_bf16(d.x, d.y);
;                     *(u32x4*)(rowp + bj * HALF) = w; }
.LBB0_356:
	v_add_f32_e32 v0, v146, v147
	s_waitcnt lgkmcnt(0)
	v_add_f32_e32 v138, v148, v149
	v_add_f32_e32 v0, v0, v138
	v_fmamk_f32 v0, v0, 0x3a800000, v224
	v_rsq_f32_e32 v0, v0
	s_mov_b32 s4, 0xbf3a00e3
	v_lshlrev_b64 v[138:139], 12, v[174:175]
	v_lshl_add_u64 v[138:139], s[20:21], 0, v[138:139]
	v_pk_mul_f32 v[134:135], v[134:135], v[0:1] op_sel_hi:[1,0]
	v_pk_mul_f32 v[140:141], v[130:131], v[0:1] op_sel_hi:[1,0]
	s_nop 0
	s_nop 0
	v_fma_f32 v130, |v134|, s64, 1.0
	v_fma_f32 v131, |v135|, s64, 1.0
	v_pk_mul_f32 v[146:147], v[134:135], v[134:135]
	v_rcp_f32_e32 v142, v130
	v_rcp_f32_e32 v143, v131
	v_mov_b64_e32 v[130:131], s[4:5]
	v_pk_mul_f32 v[146:147], v[146:147], s[76:77] op_sel_hi:[1,0]
	s_nop 0
	v_pk_fma_f32 v[144:145], v[142:143], s[66:67], v[130:131] op_sel_hi:[1,0,0]
	v_exp_f32_e32 v146, v146
	v_pk_fma_f32 v[144:145], v[142:143], v[144:145], s[70:71] op_sel_hi:[1,1,0]
	v_exp_f32_e32 v147, v147
	v_pk_fma_f32 v[144:145], v[142:143], v[144:145], s[72:73] op_sel_hi:[1,1,0]
	v_pk_mul_f32 v[136:137], v[136:137], v[0:1] op_sel_hi:[1,0]
	v_pk_fma_f32 v[144:145], v[142:143], v[144:145], s[74:75] op_sel_hi:[1,1,0]
	v_pk_mul_f32 v[132:133], v[132:133], v[0:1] op_sel_hi:[1,0]
	v_pk_mul_f32 v[142:143], v[142:143], v[144:145]
	v_pk_mul_f32 v[144:145], v[136:137], v[136:137]
	v_pk_mul_f32 v[142:143], v[146:147], v[142:143]
	v_pk_mul_f32 v[144:145], v[144:145], s[76:77] op_sel_hi:[1,0]
	v_max_f32_e32 v146, 0, v134
	v_max_f32_e32 v147, 0, v135
	v_fma_f32 v134, -|v134|, v142, v146
	v_fma_f32 v135, -|v135|, v143, v147
	v_exp_f32_e32 v144, v144
	s_nop 0
	s_nop 0
	s_nop 0
	v_exp_f32_e32 v145, v145
	s_nop 0
	s_nop 0
	v_fma_f32 v142, |v136|, s64, 1.0
	v_fma_f32 v143, |v137|, s64, 1.0
	s_nop 0
	v_rcp_f32_e32 v142, v142
	v_rcp_f32_e32 v143, v143
	v_lshl_add_u64 v[138:139], v[160:161], 1, v[138:139]
	v_pk_mul_f32 v[122:123], v[122:123], v[0:1] op_sel_hi:[1,0]
	v_pk_mul_f32 v[124:125], v[124:125], v[0:1] op_sel_hi:[1,0]
	v_pk_fma_f32 v[146:147], v[142:143], s[66:67], v[130:131] op_sel_hi:[1,0,0]
	v_pk_mul_f32 v[120:121], v[120:121], v[0:1] op_sel_hi:[1,0]
	v_pk_fma_f32 v[146:147], v[142:143], v[146:147], s[70:71] op_sel_hi:[1,1,0]
	s_nop 0
	v_pk_fma_f32 v[146:147], v[142:143], v[146:147], s[72:73] op_sel_hi:[1,1,0]
	s_nop 0
	v_pk_fma_f32 v[146:147], v[142:143], v[146:147], s[74:75] op_sel_hi:[1,1,0]
	s_nop 0
	v_pk_mul_f32 v[142:143], v[142:143], v[146:147]
	v_pk_mul_f32 v[146:147], v[140:141], v[140:141]
	v_pk_mul_f32 v[142:143], v[144:145], v[142:143]
	v_pk_mul_f32 v[146:147], v[146:147], s[76:77] op_sel_hi:[1,0]
	v_max_f32_e32 v144, 0, v136
	v_max_f32_e32 v145, 0, v137
	v_fma_f32 v136, -|v136|, v142, v144
	v_fma_f32 v137, -|v137|, v143, v145
	v_exp_f32_e32 v146, v146
	s_nop 0
	s_nop 0
	s_nop 0
	v_exp_f32_e32 v147, v147
	s_nop 0
	s_nop 0
	v_fma_f32 v142, |v140|, s64, 1.0
	v_fma_f32 v143, |v141|, s64, 1.0
	s_nop 0
	v_rcp_f32_e32 v142, v142
	v_rcp_f32_e32 v143, v143
	s_nop 0
	v_pk_fma_f32 v[144:145], v[142:143], s[66:67], v[130:131] op_sel_hi:[1,0,0]
	s_nop 0
	v_pk_fma_f32 v[144:145], v[142:143], v[144:145], s[70:71] op_sel_hi:[1,1,0]
	s_nop 0
	v_pk_fma_f32 v[144:145], v[142:143], v[144:145], s[72:73] op_sel_hi:[1,1,0]
	s_nop 0
	v_pk_fma_f32 v[144:145], v[142:143], v[144:145], s[74:75] op_sel_hi:[1,1,0]
	s_nop 0
	v_pk_mul_f32 v[142:143], v[142:143], v[144:145]
	v_pk_mul_f32 v[144:145], v[132:133], v[132:133]
	v_pk_mul_f32 v[142:143], v[146:147], v[142:143]
	v_pk_mul_f32 v[144:145], v[144:145], s[76:77] op_sel_hi:[1,0]
	v_max_f32_e32 v146, 0, v140
	v_max_f32_e32 v147, 0, v141
	v_fma_f32 v140, -|v140|, v142, v146
	v_fma_f32 v141, -|v141|, v143, v147
	v_exp_f32_e32 v144, v144
	s_nop 0
	s_nop 0
	s_nop 0
	v_exp_f32_e32 v145, v145
	s_nop 0
	s_nop 0
	v_fma_f32 v142, |v132|, s64, 1.0
	v_fma_f32 v143, |v133|, s64, 1.0
	s_nop 0
	v_rcp_f32_e32 v142, v142
	v_rcp_f32_e32 v143, v143
	s_nop 0
	v_pk_fma_f32 v[146:147], v[142:143], s[66:67], v[130:131] op_sel_hi:[1,0,0]
	s_nop 0
	v_pk_fma_f32 v[146:147], v[142:143], v[146:147], s[70:71] op_sel_hi:[1,1,0]
	s_nop 0
	v_pk_fma_f32 v[146:147], v[142:143], v[146:147], s[72:73] op_sel_hi:[1,1,0]
	s_nop 0
	v_pk_fma_f32 v[146:147], v[142:143], v[146:147], s[74:75] op_sel_hi:[1,1,0]
	s_nop 0
	v_pk_mul_f32 v[142:143], v[142:143], v[146:147]
	v_pk_mul_f32 v[146:147], v[122:123], v[122:123]
	v_pk_mul_f32 v[142:143], v[144:145], v[142:143]
	v_pk_mul_f32 v[146:147], v[146:147], s[76:77] op_sel_hi:[1,0]
	v_max_f32_e32 v144, 0, v132
	v_max_f32_e32 v145, 0, v133
	v_fma_f32 v132, -|v132|, v142, v144
	v_fma_f32 v133, -|v133|, v143, v145
	v_exp_f32_e32 v146, v146
	s_nop 0
	s_nop 0
	v_cvt_pk_bf16_f32 v142, v134, v135
	v_exp_f32_e32 v147, v147
	s_nop 0
	s_nop 0
	v_cvt_pk_bf16_f32 v143, v136, v137
	v_cvt_pk_bf16_f32 v144, v140, v141
	v_cvt_pk_bf16_f32 v145, v132, v133
	global_store_dwordx4 v[138:139], v[142:145], off
	s_nop 0
	s_nop 0
	v_pk_mul_f32 v[142:143], v[118:119], v[0:1] op_sel_hi:[1,0]
	s_nop 0
	s_nop 0
	v_fma_f32 v118, |v122|, s64, 1.0
	v_fma_f32 v119, |v123|, s64, 1.0
	s_nop 0
	v_rcp_f32_e32 v118, v118
	v_rcp_f32_e32 v119, v119
	s_nop 0
	v_pk_fma_f32 v[144:145], v[118:119], s[66:67], v[130:131] op_sel_hi:[1,0,0]
	s_nop 0
	v_pk_fma_f32 v[144:145], v[118:119], v[144:145], s[70:71] op_sel_hi:[1,1,0]
	s_nop 0
	v_pk_fma_f32 v[144:145], v[118:119], v[144:145], s[72:73] op_sel_hi:[1,1,0]
	s_nop 0
	v_pk_fma_f32 v[144:145], v[118:119], v[144:145], s[74:75] op_sel_hi:[1,1,0]
	s_nop 0
	v_pk_mul_f32 v[118:119], v[118:119], v[144:145]
; __device__ __forceinline__ unsigned cvt_pk_bf16(float lo, float hi) { unsigned r; asm volatile("v_cvt_pk_bf16_f32 %0, %1, %2" : "=v"(r) : "v"(lo), "v"(hi)); return r; }
; __device__ __forceinline__ f32x2 gelu_pk(f32x2 v) {
;     const f32x2 av = __builtin_elementwise_abs(v), d = av * 0.2316418882f + 1.0f;
;     f32x2 t; t.x = __builtin_amdgcn_rcpf(d.x); t.y = __builtin_amdgcn_rcpf(d.y);
;     f32x2 q = t * 0.5307027145f + (-0.7265760135f); q = q * t + 0.7107068705f; q = q * t + (-0.142248368f); q = q * t + 0.127414796f; q = q * t;
;     const f32x2 s = (v * v) * (-0.72134752044f);
;     f32x2 e; e.x = __builtin_amdgcn_exp2f(s.x); e.y = __builtin_amdgcn_exp2f(s.y);
;     const f32x2 m = v * (q * e), r = v - m;
;     f32x2 o; o.x = v.x < 0.f ? m.x : r.x; o.y = v.y < 0.f ? m.y : r.y; return o;
; }
;     __device__ __forceinline__ void operator()(const f32x4 (&acc)[2][2][4][2], const Unit& u, int wr, int wc, int fr, int fq) const {
;     ...
;             for (int m = 0; m < 4; ++m) { const int row = row0 + ai * HALF + m * 16; const float rs = rsv[ai][m]; bf16_t* rowp = O + (size_t)row * ldc + col0; float s1 = 0.f, s2 = 0.f;
; #pragma unroll
;                 for (int bj = 0; bj < 2; ++bj) { f32x4 v0 = acc[ai][bj][m][0] * rs, v1 = acc[ai][bj][m][1] * rs;
;                     const f32x2 a = gelu_pk((f32x2){v0[0], v0[1]}), b = gelu_pk((f32x2){v0[2], v0[3]}), c = gelu_pk((f32x2){v1[0], v1[1]}), d = gelu_pk((f32x2){v1[2], v1[3]});
;                     s1 += ((a.x + a.y) + (b.x + b.y)) + ((c.x + c.y) + (d.x + d.y));
;                     s2 += ((a.x * a.x + a.y * a.y) + (b.x * b.x + b.y * b.y)) + ((c.x * c.x + c.y * c.y) + (d.x * d.x + d.y * d.y));
;                     u32x4 w; w.x = cvt_pk_bf16(a.x, a.y); w.y = cvt_pk_bf16(b.x, b.y); w.z = cvt_pk_bf16(c.x, c.y); w.w = cvt_pk_bf16(d.x, d.y);
;                     *(u32x4*)(rowp + bj * HALF) = w; }
;                 if (isv) { s1 += __shfl_xor(s1, 16); s1 += __shfl_xor(s1, 32); s2 += __shfl_xor(s2, 16); s2 += __shfl_xor(s2, 32);
;                     if (fq == 0) { const int rl = ai * HALF + wr * 64 + m * 16 + fr; part[rl * 4 + wc] = s1; part[1024 + rl * 4 + wc] = s2; } } }
	v_pk_mul_f32 v[144:145], v[124:125], v[124:125]
	v_pk_mul_f32 v[118:119], v[146:147], v[118:119]
	v_pk_mul_f32 v[144:145], v[144:145], s[76:77] op_sel_hi:[1,0]
	v_max_f32_e32 v146, 0, v122
	v_max_f32_e32 v147, 0, v123
	v_fma_f32 v0, -|v122|, v118, v146
	v_fma_f32 v118, -|v123|, v119, v147
	s_nop 0
	s_nop 0
	s_nop 0
	s_nop 0
	v_fma_f32 v122, |v124|, s64, 1.0
	v_fma_f32 v123, |v125|, s64, 1.0
	s_nop 0
	v_rcp_f32_e32 v122, v122
	v_rcp_f32_e32 v123, v123
	v_exp_f32_e32 v144, v144
	v_exp_f32_e32 v145, v145
	s_nop 0
	v_pk_fma_f32 v[146:147], v[122:123], s[66:67], v[130:131] op_sel_hi:[1,0,0]
	s_nop 0
	v_pk_fma_f32 v[146:147], v[122:123], v[146:147], s[70:71] op_sel_hi:[1,1,0]
	s_nop 0
	v_pk_fma_f32 v[146:147], v[122:123], v[146:147], s[72:73] op_sel_hi:[1,1,0]
	s_nop 0
	v_pk_fma_f32 v[146:147], v[122:123], v[146:147], s[74:75] op_sel_hi:[1,1,0]
	s_nop 0
	v_pk_mul_f32 v[122:123], v[122:123], v[146:147]
	v_pk_mul_f32 v[146:147], v[142:143], v[142:143]
	v_pk_mul_f32 v[122:123], v[144:145], v[122:123]
	v_pk_mul_f32 v[146:147], v[146:147], s[76:77] op_sel_hi:[1,0]
	v_max_f32_e32 v144, 0, v124
	v_max_f32_e32 v145, 0, v125
	v_fma_f32 v119, -|v124|, v122, v144
	v_fma_f32 v122, -|v125|, v123, v145
	s_nop 0
	s_nop 0
	s_nop 0
	s_nop 0
	v_fma_f32 v124, |v142|, s64, 1.0
	v_fma_f32 v125, |v143|, s64, 1.0
	s_nop 0
	v_rcp_f32_e32 v124, v124
	v_rcp_f32_e32 v125, v125
	v_exp_f32_e32 v146, v146
	v_exp_f32_e32 v147, v147
	s_nop 0
	v_pk_fma_f32 v[144:145], v[124:125], s[66:67], v[130:131] op_sel_hi:[1,0,0]
	s_nop 0
	v_pk_fma_f32 v[144:145], v[124:125], v[144:145], s[70:71] op_sel_hi:[1,1,0]
	s_nop 0
	v_pk_fma_f32 v[144:145], v[124:125], v[144:145], s[72:73] op_sel_hi:[1,1,0]
	s_nop 0
	v_pk_fma_f32 v[144:145], v[124:125], v[144:145], s[74:75] op_sel_hi:[1,1,0]
	s_nop 0
	v_pk_mul_f32 v[124:125], v[124:125], v[144:145]
	v_pk_mul_f32 v[144:145], v[120:121], v[120:121]
	v_pk_mul_f32 v[124:125], v[146:147], v[124:125]
	s_nop 0
	v_max_f32_e32 v146, 0, v142
	v_max_f32_e32 v147, 0, v143
	v_fma_f32 v123, -|v142|, v124, v146
	v_fma_f32 v124, -|v143|, v125, v147
	s_nop 0
	s_nop 0
	s_nop 0
	s_nop 0
	v_fma_f32 v142, |v120|, s64, 1.0
	v_fma_f32 v143, |v121|, s64, 1.0
	s_nop 0
	v_rcp_f32_e32 v142, v142
	v_rcp_f32_e32 v143, v143
	s_nop 0
	v_cndmask_b32_e64 v125, 0, 1, s[36:37]
	v_cmp_ne_u32_e64 s[10:11], 1, v125
	v_pk_fma_f32 v[130:131], v[142:143], s[66:67], v[130:131] op_sel_hi:[1,0,0]
	s_nop 0
	v_pk_fma_f32 v[130:131], v[142:143], v[130:131], s[70:71] op_sel_hi:[1,1,0]
	s_nop 0
	v_pk_fma_f32 v[130:131], v[142:143], v[130:131], s[72:73] op_sel_hi:[1,1,0]
	s_nop 0
	v_pk_fma_f32 v[130:131], v[142:143], v[130:131], s[74:75] op_sel_hi:[1,1,0]
	s_nop 0
	v_pk_mul_f32 v[130:131], v[142:143], v[130:131]
	v_pk_mul_f32 v[142:143], v[144:145], s[76:77] op_sel_hi:[1,0]
	s_nop 0
	v_exp_f32_e32 v142, v142
	v_exp_f32_e32 v143, v143
	s_nop 0
	v_pk_mul_f32 v[130:131], v[142:143], v[130:131]
	s_nop 0
	v_max_f32_e32 v142, 0, v120
	v_max_f32_e32 v143, 0, v121
	v_fma_f32 v120, -|v120|, v130, v142
	v_fma_f32 v121, -|v121|, v131, v143
	s_nop 0
	s_nop 0
	s_nop 0
	v_cvt_pk_bf16_f32 v142, v0, v118
	s_nop 1
	s_nop 0
	s_andn2_b64 vcc, exec, s[36:37]
	v_cvt_pk_bf16_f32 v143, v119, v122
	v_cvt_pk_bf16_f32 v144, v123, v124
	v_cvt_pk_bf16_f32 v145, v120, v121
	global_store_dwordx4 v[138:139], v[142:145], off offset:256
	s_cbranch_vccnz .LBB0_360
	v_mul_f32_e32 v125, v135, v135
	v_mul_f32_e32 v130, v137, v137
	v_fmac_f32_e32 v125, v134, v134
	v_fmac_f32_e32 v130, v136, v136
	v_add_f32_e32 v125, v125, v130
	v_mul_f32_e32 v130, v141, v141
	v_mul_f32_e32 v131, v133, v133
	v_fmac_f32_e32 v130, v140, v140
	v_fmac_f32_e32 v131, v132, v132
	v_add_f32_e32 v130, v130, v131
	v_add_f32_e32 v125, v125, v130
	v_mul_f32_e32 v130, v118, v118
	v_fmac_f32_e32 v130, v0, v0
	v_mul_f32_e32 v131, v122, v122
	v_add_f32_e32 v0, v0, v118
	v_add_f32_e32 v118, v119, v122
	v_fmac_f32_e32 v131, v119, v119
	v_add_f32_e32 v134, v134, v135
	v_add_f32_e32 v135, v136, v137
	v_add_f32_e32 v0, v0, v118
	v_add_f32_e32 v118, v123, v124
	v_add_f32_e32 v119, v120, v121
	v_add_f32_e32 v134, v134, v135
	v_add_f32_e32 v135, v140, v141
	v_add_f32_e32 v132, v132, v133
	v_add_f32_e32 v118, v118, v119
	v_and_b32_e32 v119, 64, v226
	v_add_f32_e32 v132, v135, v132
	v_add_f32_e32 v0, v0, v118
	v_xor_b32_e32 v118, 16, v226
	v_add_u32_e32 v119, 64, v119
	v_add_f32_e32 v132, v134, v132
	v_cmp_lt_i32_e32 vcc, v118, v119
	v_add_f32_e32 v130, v130, v131
	v_mul_f32_e32 v131, v124, v124
	v_mul_f32_e32 v138, v121, v121
	v_add_f32_e32 v132, 0, v132
	v_cndmask_b32_e32 v118, v226, v118, vcc
	v_fmac_f32_e32 v131, v123, v123
	v_add_f32_e32 v0, v0, v132
	v_lshlrev_b32_e32 v118, 2, v118
	v_fmac_f32_e32 v138, v120, v120
	v_mov_b32_e32 v121, v0
	s_nop 1
	v_permlane16_swap_b32_e32 v121, v0
	v_add_f32_e32 v120, v131, v138
	v_add_f32_e32 v120, v130, v120
	v_add_f32_e32 v120, v125, v120
	v_mov_b32_e32 v122, v120
	s_nop 1
	v_permlane16_swap_b32_e32 v122, v120
	s_waitcnt lgkmcnt(0)
	v_add_f32_e32 v0, v0, v121
	v_xor_b32_e32 v121, 32, v226
	v_cmp_lt_i32_e32 vcc, v121, v119
	v_add_f32_e32 v119, v120, v122
	s_nop 0
	v_cndmask_b32_e32 v118, v226, v121, vcc
	v_lshlrev_b32_e32 v121, 2, v118
	v_mov_b32_e32 v118, v0
	s_nop 1
	v_permlane32_swap_b32_e32 v118, v0
	v_mov_b32_e32 v120, v119
	s_nop 1
	v_permlane32_swap_b32_e32 v120, v119
	s_and_saveexec_b64 s[4:5], s[6:7]
	s_cbranch_execz .LBB0_359
	s_waitcnt lgkmcnt(0)
	v_add_f32_e32 v119, v119, v120
	v_add_f32_e32 v0, v0, v118
	ds_write2st64_b32 v186, v0, v119 offset0:1 offset1:17

; __device__ __forceinline__ unsigned cvt_pk_bf16(float lo, float hi) { unsigned r; asm volatile("v_cvt_pk_bf16_f32 %0, %1, %2" : "=v"(r) : "v"(lo), "v"(hi)); return r; }
; __device__ __forceinline__ f32x2 gelu_pk(f32x2 v) {
;     const f32x2 av = __builtin_elementwise_abs(v), d = av * 0.2316418882f + 1.0f;
;     f32x2 t; t.x = __builtin_amdgcn_rcpf(d.x); t.y = __builtin_amdgcn_rcpf(d.y);
;     f32x2 q = t * 0.5307027145f + (-0.7265760135f); q = q * t + 0.7107068705f; q = q * t + (-0.142248368f); q = q * t + 0.127414796f; q = q * t;
;     const f32x2 s = (v * v) * (-0.72134752044f);
;     f32x2 e; e.x = __builtin_amdgcn_exp2f(s.x); e.y = __builtin_amdgcn_exp2f(s.y);
;     const f32x2 m = v * (q * e), r = v - m;
;     f32x2 o; o.x = v.x < 0.f ? m.x : r.x; o.y = v.y < 0.f ? m.y : r.y; return o;
; }
;     __device__ __forceinline__ void operator()(const f32x4 (&acc)[2][2][4][2], const Unit& u, int wr, int wc, int fr, int fq) const {
;     ...
;             for (int m = 0; m < 4; ++m) { const int row = row0 + ai * HALF + m * 16; const float rs = rsv[ai][m]; bf16_t* rowp = O + (size_t)row * ldc + col0; float s1 = 0.f, s2 = 0.f;
; #pragma unroll
;                 for (int bj = 0; bj < 2; ++bj) { f32x4 v0 = acc[ai][bj][m][0] * rs, v1 = acc[ai][bj][m][1] * rs;
;                     const f32x2 a = gelu_pk((f32x2){v0[0], v0[1]}), b = gelu_pk((f32x2){v0[2], v0[3]}), c = gelu_pk((f32x2){v1[0], v1[1]}), d = gelu_pk((f32x2){v1[2], v1[3]});
;                     s1 += ((a.x + a.y) + (b.x + b.y)) + ((c.x + c.y) + (d.x + d.y));
;                     s2 += ((a.x * a.x + a.y * a.y) + (b.x * b.x + b.y * b.y)) + ((c.x * c.x + c.y * c.y) + (d.x * d.x + d.y * d.y));
;                     u32x4 w; w.x = cvt_pk_bf16(a.x, a.y); w.y = cvt_pk_bf16(b.x, b.y); w.z = cvt_pk_bf16(c.x, c.y); w.w = cvt_pk_bf16(d.x, d.y);
;                     *(u32x4*)(rowp + bj * HALF) = w; }
.LBB0_360:
	v_add_f32_e32 v0, v126, v127
	s_waitcnt lgkmcnt(0)
	v_add_f32_e32 v118, v128, v129
	v_add_f32_e32 v0, v0, v118
	v_fmamk_f32 v0, v0, 0x3a800000, v224
	v_rsq_f32_e32 v0, v0
	s_mov_b32 s4, 0xbf3a00e3
	v_lshlrev_b64 v[118:119], 12, v[172:173]
	v_lshl_add_u64 v[118:119], s[20:21], 0, v[118:119]
	v_pk_mul_f32 v[114:115], v[114:115], v[0:1] op_sel_hi:[1,0]
	v_pk_mul_f32 v[120:121], v[106:107], v[0:1] op_sel_hi:[1,0]
	s_nop 0
	s_nop 0
	v_fma_f32 v106, |v114|, s64, 1.0
	v_fma_f32 v107, |v115|, s64, 1.0
	v_pk_mul_f32 v[126:127], v[114:115], v[114:115]
	v_rcp_f32_e32 v122, v106
	v_rcp_f32_e32 v123, v107
	v_mov_b64_e32 v[106:107], s[4:5]
	v_pk_mul_f32 v[126:127], v[126:127], s[76:77] op_sel_hi:[1,0]
	s_nop 0
	v_pk_fma_f32 v[124:125], v[122:123], s[66:67], v[106:107] op_sel_hi:[1,0,0]
	v_exp_f32_e32 v126, v126
	v_pk_fma_f32 v[124:125], v[122:123], v[124:125], s[70:71] op_sel_hi:[1,1,0]
	v_exp_f32_e32 v127, v127
	v_pk_fma_f32 v[124:125], v[122:123], v[124:125], s[72:73] op_sel_hi:[1,1,0]
	v_pk_mul_f32 v[116:117], v[116:117], v[0:1] op_sel_hi:[1,0]
	v_pk_fma_f32 v[124:125], v[122:123], v[124:125], s[74:75] op_sel_hi:[1,1,0]
	v_pk_mul_f32 v[108:109], v[108:109], v[0:1] op_sel_hi:[1,0]
	v_pk_mul_f32 v[122:123], v[122:123], v[124:125]
	v_pk_mul_f32 v[124:125], v[116:117], v[116:117]
	v_pk_mul_f32 v[122:123], v[126:127], v[122:123]
	v_pk_mul_f32 v[124:125], v[124:125], s[76:77] op_sel_hi:[1,0]
	v_max_f32_e32 v126, 0, v114
	v_max_f32_e32 v127, 0, v115
	v_fma_f32 v114, -|v114|, v122, v126
	v_fma_f32 v115, -|v115|, v123, v127
	v_exp_f32_e32 v124, v124
	s_nop 0
	s_nop 0
	s_nop 0
	v_exp_f32_e32 v125, v125
	s_nop 0
	s_nop 0
	v_fma_f32 v122, |v116|, s64, 1.0
	v_fma_f32 v123, |v117|, s64, 1.0
	s_nop 0
	v_rcp_f32_e32 v122, v122
	v_rcp_f32_e32 v123, v123
	v_lshl_add_u64 v[118:119], v[160:161], 1, v[118:119]
	v_pk_mul_f32 v[102:103], v[102:103], v[0:1] op_sel_hi:[1,0]
	v_pk_mul_f32 v[104:105], v[104:105], v[0:1] op_sel_hi:[1,0]
	v_pk_fma_f32 v[126:127], v[122:123], s[66:67], v[106:107] op_sel_hi:[1,0,0]
	v_pk_mul_f32 v[100:101], v[100:101], v[0:1] op_sel_hi:[1,0]
	v_pk_fma_f32 v[126:127], v[122:123], v[126:127], s[70:71] op_sel_hi:[1,1,0]
	s_nop 0
	v_pk_fma_f32 v[126:127], v[122:123], v[126:127], s[72:73] op_sel_hi:[1,1,0]
	s_nop 0
	v_pk_fma_f32 v[126:127], v[122:123], v[126:127], s[74:75] op_sel_hi:[1,1,0]
	s_nop 0
	v_pk_mul_f32 v[122:123], v[122:123], v[126:127]
	v_pk_mul_f32 v[126:127], v[120:121], v[120:121]
	v_pk_mul_f32 v[122:123], v[124:125], v[122:123]
	v_pk_mul_f32 v[126:127], v[126:127], s[76:77] op_sel_hi:[1,0]
	v_max_f32_e32 v124, 0, v116
	v_max_f32_e32 v125, 0, v117
	v_fma_f32 v116, -|v116|, v122, v124
	v_fma_f32 v117, -|v117|, v123, v125
	v_exp_f32_e32 v126, v126
	s_nop 0
	s_nop 0
	s_nop 0
	v_exp_f32_e32 v127, v127
	s_nop 0
	s_nop 0
	v_fma_f32 v122, |v120|, s64, 1.0
	v_fma_f32 v123, |v121|, s64, 1.0
	s_nop 0
	v_rcp_f32_e32 v122, v122
	v_rcp_f32_e32 v123, v123
	s_nop 0
	v_pk_fma_f32 v[124:125], v[122:123], s[66:67], v[106:107] op_sel_hi:[1,0,0]
	s_nop 0
	v_pk_fma_f32 v[124:125], v[122:123], v[124:125], s[70:71] op_sel_hi:[1,1,0]
	s_nop 0
	v_pk_fma_f32 v[124:125], v[122:123], v[124:125], s[72:73] op_sel_hi:[1,1,0]
	s_nop 0
	v_pk_fma_f32 v[124:125], v[122:123], v[124:125], s[74:75] op_sel_hi:[1,1,0]
	s_nop 0
	v_pk_mul_f32 v[122:123], v[122:123], v[124:125]
	v_pk_mul_f32 v[124:125], v[108:109], v[108:109]
	v_pk_mul_f32 v[122:123], v[126:127], v[122:123]
	v_pk_mul_f32 v[124:125], v[124:125], s[76:77] op_sel_hi:[1,0]
	v_max_f32_e32 v126, 0, v120
	v_max_f32_e32 v127, 0, v121
	v_fma_f32 v120, -|v120|, v122, v126
	v_fma_f32 v121, -|v121|, v123, v127
	v_exp_f32_e32 v124, v124
	s_nop 0
	s_nop 0
	s_nop 0
	v_exp_f32_e32 v125, v125
	s_nop 0
	s_nop 0
	v_fma_f32 v122, |v108|, s64, 1.0
	v_fma_f32 v123, |v109|, s64, 1.0
	s_nop 0
	v_rcp_f32_e32 v122, v122
	v_rcp_f32_e32 v123, v123
	s_nop 0
	v_pk_fma_f32 v[126:127], v[122:123], s[66:67], v[106:107] op_sel_hi:[1,0,0]
	s_nop 0
	v_pk_fma_f32 v[126:127], v[122:123], v[126:127], s[70:71] op_sel_hi:[1,1,0]
	s_nop 0
	v_pk_fma_f32 v[126:127], v[122:123], v[126:127], s[72:73] op_sel_hi:[1,1,0]
	s_nop 0
	v_pk_fma_f32 v[126:127], v[122:123], v[126:127], s[74:75] op_sel_hi:[1,1,0]
	s_nop 0
	v_pk_mul_f32 v[122:123], v[122:123], v[126:127]
	v_pk_mul_f32 v[126:127], v[102:103], v[102:103]
	v_pk_mul_f32 v[122:123], v[124:125], v[122:123]
	v_pk_mul_f32 v[126:127], v[126:127], s[76:77] op_sel_hi:[1,0]
	v_max_f32_e32 v124, 0, v108
	v_max_f32_e32 v125, 0, v109
	v_fma_f32 v108, -|v108|, v122, v124
	v_fma_f32 v109, -|v109|, v123, v125
	v_exp_f32_e32 v126, v126
	s_nop 0
	s_nop 0
	v_cvt_pk_bf16_f32 v122, v114, v115
	v_exp_f32_e32 v127, v127
	s_nop 0
	s_nop 0
	v_cvt_pk_bf16_f32 v123, v116, v117
	v_cvt_pk_bf16_f32 v124, v120, v121
	v_cvt_pk_bf16_f32 v125, v108, v109
	global_store_dwordx4 v[118:119], v[122:125], off
	s_nop 0
	s_nop 0
	v_pk_mul_f32 v[122:123], v[98:99], v[0:1] op_sel_hi:[1,0]
	s_nop 0
	s_nop 0
	v_fma_f32 v98, |v102|, s64, 1.0
	v_fma_f32 v99, |v103|, s64, 1.0
	s_nop 0
	v_rcp_f32_e32 v98, v98
	v_rcp_f32_e32 v99, v99
	s_nop 0
	v_pk_fma_f32 v[124:125], v[98:99], s[66:67], v[106:107] op_sel_hi:[1,0,0]
	s_nop 0
	v_pk_fma_f32 v[124:125], v[98:99], v[124:125], s[70:71] op_sel_hi:[1,1,0]
	s_nop 0
	v_pk_fma_f32 v[124:125], v[98:99], v[124:125], s[72:73] op_sel_hi:[1,1,0]
	s_nop 0
	v_pk_fma_f32 v[124:125], v[98:99], v[124:125], s[74:75] op_sel_hi:[1,1,0]
	s_nop 0
; __device__ __forceinline__ unsigned cvt_pk_bf16(float lo, float hi) { unsigned r; asm volatile("v_cvt_pk_bf16_f32 %0, %1, %2" : "=v"(r) : "v"(lo), "v"(hi)); return r; }
; __device__ __forceinline__ f32x2 gelu_pk(f32x2 v) {
;     const f32x2 av = __builtin_elementwise_abs(v), d = av * 0.2316418882f + 1.0f;
;     f32x2 t; t.x = __builtin_amdgcn_rcpf(d.x); t.y = __builtin_amdgcn_rcpf(d.y);
;     f32x2 q = t * 0.5307027145f + (-0.7265760135f); q = q * t + 0.7107068705f; q = q * t + (-0.142248368f); q = q * t + 0.127414796f; q = q * t;
;     const f32x2 s = (v * v) * (-0.72134752044f);
;     f32x2 e; e.x = __builtin_amdgcn_exp2f(s.x); e.y = __builtin_amdgcn_exp2f(s.y);
;     const f32x2 m = v * (q * e), r = v - m;
;     f32x2 o; o.x = v.x < 0.f ? m.x : r.x; o.y = v.y < 0.f ? m.y : r.y; return o;
; }
;     __device__ __forceinline__ void operator()(const f32x4 (&acc)[2][2][4][2], const Unit& u, int wr, int wc, int fr, int fq) const {
;     ...
;                 for (int bj = 0; bj < 2; ++bj) { f32x4 v0 = acc[ai][bj][m][0] * rs, v1 = acc[ai][bj][m][1] * rs;
;                     const f32x2 a = gelu_pk((f32x2){v0[0], v0[1]}), b = gelu_pk((f32x2){v0[2], v0[3]}), c = gelu_pk((f32x2){v1[0], v1[1]}), d = gelu_pk((f32x2){v1[2], v1[3]});
;                     s1 += ((a.x + a.y) + (b.x + b.y)) + ((c.x + c.y) + (d.x + d.y));
;                     s2 += ((a.x * a.x + a.y * a.y) + (b.x * b.x + b.y * b.y)) + ((c.x * c.x + c.y * c.y) + (d.x * d.x + d.y * d.y));
;                     u32x4 w; w.x = cvt_pk_bf16(a.x, a.y); w.y = cvt_pk_bf16(b.x, b.y); w.z = cvt_pk_bf16(c.x, c.y); w.w = cvt_pk_bf16(d.x, d.y);
;                     *(u32x4*)(rowp + bj * HALF) = w; }
;                 if (isv) { s1 += __shfl_xor(s1, 16); s1 += __shfl_xor(s1, 32); s2 += __shfl_xor(s2, 16); s2 += __shfl_xor(s2, 32);
;                     if (fq == 0) { const int rl = ai * HALF + wr * 64 + m * 16 + fr; part[rl * 4 + wc] = s1; part[1024 + rl * 4 + wc] = s2; } } }
	v_pk_mul_f32 v[98:99], v[98:99], v[124:125]
	v_pk_mul_f32 v[124:125], v[104:105], v[104:105]
	v_pk_mul_f32 v[98:99], v[126:127], v[98:99]
	v_pk_mul_f32 v[124:125], v[124:125], s[76:77] op_sel_hi:[1,0]
	v_max_f32_e32 v126, 0, v102
	v_max_f32_e32 v127, 0, v103
	v_fma_f32 v0, -|v102|, v98, v126
	v_fma_f32 v98, -|v103|, v99, v127
	s_nop 0
	s_nop 0
	s_nop 0
	s_nop 0
	v_fma_f32 v102, |v104|, s64, 1.0
	v_fma_f32 v103, |v105|, s64, 1.0
	s_nop 0
	v_rcp_f32_e32 v102, v102
	v_rcp_f32_e32 v103, v103
	v_exp_f32_e32 v124, v124
	v_exp_f32_e32 v125, v125
	s_nop 0
	v_pk_fma_f32 v[126:127], v[102:103], s[66:67], v[106:107] op_sel_hi:[1,0,0]
	s_nop 0
	v_pk_fma_f32 v[126:127], v[102:103], v[126:127], s[70:71] op_sel_hi:[1,1,0]
	s_nop 0
	v_pk_fma_f32 v[126:127], v[102:103], v[126:127], s[72:73] op_sel_hi:[1,1,0]
	s_nop 0
	v_pk_fma_f32 v[126:127], v[102:103], v[126:127], s[74:75] op_sel_hi:[1,1,0]
	s_nop 0
	v_pk_mul_f32 v[102:103], v[102:103], v[126:127]
	v_pk_mul_f32 v[126:127], v[122:123], v[122:123]
	v_pk_mul_f32 v[102:103], v[124:125], v[102:103]
	v_pk_mul_f32 v[126:127], v[126:127], s[76:77] op_sel_hi:[1,0]
	v_max_f32_e32 v124, 0, v104
	v_max_f32_e32 v125, 0, v105
	v_fma_f32 v99, -|v104|, v102, v124
	v_fma_f32 v102, -|v105|, v103, v125
	s_nop 0
	s_nop 0
	s_nop 0
	s_nop 0
	v_fma_f32 v104, |v122|, s64, 1.0
	v_fma_f32 v105, |v123|, s64, 1.0
	s_nop 0
	v_rcp_f32_e32 v104, v104
	v_rcp_f32_e32 v105, v105
	v_exp_f32_e32 v126, v126
	v_exp_f32_e32 v127, v127
	s_nop 0
	v_pk_fma_f32 v[124:125], v[104:105], s[66:67], v[106:107] op_sel_hi:[1,0,0]
	s_nop 0
	v_pk_fma_f32 v[124:125], v[104:105], v[124:125], s[70:71] op_sel_hi:[1,1,0]
	s_nop 0
	v_pk_fma_f32 v[124:125], v[104:105], v[124:125], s[72:73] op_sel_hi:[1,1,0]
	s_nop 0
	v_pk_fma_f32 v[124:125], v[104:105], v[124:125], s[74:75] op_sel_hi:[1,1,0]
	s_nop 0
	v_pk_mul_f32 v[104:105], v[104:105], v[124:125]
	v_pk_mul_f32 v[124:125], v[100:101], v[100:101]
	v_pk_mul_f32 v[104:105], v[126:127], v[104:105]
	s_nop 0
	v_max_f32_e32 v126, 0, v122
	v_max_f32_e32 v127, 0, v123
	v_fma_f32 v103, -|v122|, v104, v126
	v_fma_f32 v104, -|v123|, v105, v127
	s_nop 0
	s_nop 0
	s_nop 0
	s_nop 0
	v_fma_f32 v122, |v100|, s64, 1.0
	v_fma_f32 v123, |v101|, s64, 1.0
	s_nop 0
	v_rcp_f32_e32 v122, v122
	v_rcp_f32_e32 v123, v123
	s_nop 0
	v_pk_fma_f32 v[106:107], v[122:123], s[66:67], v[106:107] op_sel_hi:[1,0,0]
	s_nop 0
	v_pk_fma_f32 v[106:107], v[122:123], v[106:107], s[70:71] op_sel_hi:[1,1,0]
	s_nop 0
	v_pk_fma_f32 v[106:107], v[122:123], v[106:107], s[72:73] op_sel_hi:[1,1,0]
	s_nop 0
	v_pk_fma_f32 v[106:107], v[122:123], v[106:107], s[74:75] op_sel_hi:[1,1,0]
	s_nop 0
	v_pk_mul_f32 v[106:107], v[122:123], v[106:107]
	v_pk_mul_f32 v[122:123], v[124:125], s[76:77] op_sel_hi:[1,0]
	s_nop 0
	v_exp_f32_e32 v122, v122
	v_exp_f32_e32 v123, v123
	s_nop 0
	v_pk_mul_f32 v[106:107], v[122:123], v[106:107]
	s_nop 0
	v_max_f32_e32 v122, 0, v100
	v_max_f32_e32 v123, 0, v101
	v_fma_f32 v100, -|v100|, v106, v122
	v_fma_f32 v101, -|v101|, v107, v123
	s_nop 0
	s_nop 0
	s_nop 0
	v_cvt_pk_bf16_f32 v122, v0, v98
	s_nop 1
	s_nop 0
	s_and_b64 vcc, exec, s[10:11]
	v_cvt_pk_bf16_f32 v123, v99, v102
	v_cvt_pk_bf16_f32 v124, v103, v104
	v_cvt_pk_bf16_f32 v125, v100, v101
	global_store_dwordx4 v[118:119], v[122:125], off offset:256
	s_cbranch_vccnz .LBB0_364
	v_mul_f32_e32 v105, v115, v115
	v_mul_f32_e32 v106, v117, v117
	v_fmac_f32_e32 v105, v114, v114
	v_fmac_f32_e32 v106, v116, v116
	v_add_f32_e32 v105, v105, v106
	v_mul_f32_e32 v106, v121, v121
	v_mul_f32_e32 v107, v109, v109
	v_fmac_f32_e32 v106, v120, v120
	v_fmac_f32_e32 v107, v108, v108
	v_add_f32_e32 v106, v106, v107
	v_add_f32_e32 v105, v105, v106
	v_mul_f32_e32 v106, v98, v98
	v_fmac_f32_e32 v106, v0, v0
	v_mul_f32_e32 v107, v102, v102
	v_add_f32_e32 v0, v0, v98
	v_add_f32_e32 v98, v99, v102
	v_fmac_f32_e32 v107, v99, v99
	v_add_f32_e32 v114, v114, v115
	v_add_f32_e32 v115, v116, v117
	v_add_f32_e32 v0, v0, v98
	v_add_f32_e32 v98, v103, v104
	v_add_f32_e32 v99, v100, v101
	v_add_f32_e32 v114, v114, v115
	v_add_f32_e32 v115, v120, v121
	v_add_f32_e32 v108, v108, v109
	v_add_f32_e32 v98, v98, v99
	v_and_b32_e32 v99, 64, v226
	v_add_f32_e32 v108, v115, v108
	v_add_f32_e32 v0, v0, v98
	v_xor_b32_e32 v98, 16, v226
	v_add_u32_e32 v99, 64, v99
	v_add_f32_e32 v108, v114, v108
	v_cmp_lt_i32_e32 vcc, v98, v99
	v_add_f32_e32 v106, v106, v107
	v_mul_f32_e32 v107, v104, v104
	v_mul_f32_e32 v118, v101, v101
	v_add_f32_e32 v108, 0, v108
	v_cndmask_b32_e32 v98, v226, v98, vcc
	v_fmac_f32_e32 v107, v103, v103
	v_add_f32_e32 v0, v0, v108
	v_lshlrev_b32_e32 v98, 2, v98
	v_fmac_f32_e32 v118, v100, v100
	v_mov_b32_e32 v101, v0
	s_nop 1
	v_permlane16_swap_b32_e32 v101, v0
	v_add_f32_e32 v100, v107, v118
	v_add_f32_e32 v100, v106, v100
	v_add_f32_e32 v100, v105, v100
	v_mov_b32_e32 v102, v100
	s_nop 1
	v_permlane16_swap_b32_e32 v102, v100
	s_waitcnt lgkmcnt(0)
	v_add_f32_e32 v0, v0, v101
	v_xor_b32_e32 v101, 32, v226
	v_cmp_lt_i32_e32 vcc, v101, v99
	v_add_f32_e32 v99, v100, v102
	s_nop 0
	v_cndmask_b32_e32 v98, v226, v101, vcc
	v_lshlrev_b32_e32 v101, 2, v98
	v_mov_b32_e32 v98, v0
	s_nop 1
	v_permlane32_swap_b32_e32 v98, v0
	v_mov_b32_e32 v100, v99
	s_nop 1
	v_permlane32_swap_b32_e32 v100, v99
	s_and_saveexec_b64 s[4:5], s[6:7]
	s_cbranch_execz .LBB0_363
	s_waitcnt lgkmcnt(0)
	v_add_f32_e32 v99, v99, v100
	v_add_f32_e32 v0, v0, v98
	ds_write2st64_b32 v186, v0, v99 offset0:2 offset1:18

; __device__ __forceinline__ unsigned cvt_pk_bf16(float lo, float hi) { unsigned r; asm volatile("v_cvt_pk_bf16_f32 %0, %1, %2" : "=v"(r) : "v"(lo), "v"(hi)); return r; }
; __device__ __forceinline__ f32x2 gelu_pk(f32x2 v) {
;     const f32x2 av = __builtin_elementwise_abs(v), d = av * 0.2316418882f + 1.0f;
;     f32x2 t; t.x = __builtin_amdgcn_rcpf(d.x); t.y = __builtin_amdgcn_rcpf(d.y);
;     f32x2 q = t * 0.5307027145f + (-0.7265760135f); q = q * t + 0.7107068705f; q = q * t + (-0.142248368f); q = q * t + 0.127414796f; q = q * t;
;     const f32x2 s = (v * v) * (-0.72134752044f);
;     f32x2 e; e.x = __builtin_amdgcn_exp2f(s.x); e.y = __builtin_amdgcn_exp2f(s.y);
;     const f32x2 m = v * (q * e), r = v - m;
;     f32x2 o; o.x = v.x < 0.f ? m.x : r.x; o.y = v.y < 0.f ? m.y : r.y; return o;
; }
;     __device__ __forceinline__ void operator()(const f32x4 (&acc)[2][2][4][2], const Unit& u, int wr, int wc, int fr, int fq) const {
;     ...
;             for (int m = 0; m < 4; ++m) { const int row = row0 + ai * HALF + m * 16; const float rs = rsv[ai][m]; bf16_t* rowp = O + (size_t)row * ldc + col0; float s1 = 0.f, s2 = 0.f;
; #pragma unroll
;                 for (int bj = 0; bj < 2; ++bj) { f32x4 v0 = acc[ai][bj][m][0] * rs, v1 = acc[ai][bj][m][1] * rs;
;                     const f32x2 a = gelu_pk((f32x2){v0[0], v0[1]}), b = gelu_pk((f32x2){v0[2], v0[3]}), c = gelu_pk((f32x2){v1[0], v1[1]}), d = gelu_pk((f32x2){v1[2], v1[3]});
;                     s1 += ((a.x + a.y) + (b.x + b.y)) + ((c.x + c.y) + (d.x + d.y));
;                     s2 += ((a.x * a.x + a.y * a.y) + (b.x * b.x + b.y * b.y)) + ((c.x * c.x + c.y * c.y) + (d.x * d.x + d.y * d.y));
;                     u32x4 w; w.x = cvt_pk_bf16(a.x, a.y); w.y = cvt_pk_bf16(b.x, b.y); w.z = cvt_pk_bf16(c.x, c.y); w.w = cvt_pk_bf16(d.x, d.y);
;                     *(u32x4*)(rowp + bj * HALF) = w; }
.LBB0_364:
	v_add_f32_e32 v0, v110, v111
	s_waitcnt lgkmcnt(0)
	v_add_f32_e32 v98, v112, v113
	v_add_f32_e32 v0, v0, v98
	v_fmamk_f32 v0, v0, 0x3a800000, v224
	v_rsq_f32_e32 v0, v0
	s_mov_b32 s4, 0xbf3a00e3
	v_lshlrev_b64 v[98:99], 12, v[170:171]
	v_lshl_add_u64 v[98:99], s[20:21], 0, v[98:99]
	v_pk_mul_f32 v[90:91], v[90:91], v[0:1] op_sel_hi:[1,0]
	v_pk_mul_f32 v[100:101], v[86:87], v[0:1] op_sel_hi:[1,0]
	s_nop 0
	s_nop 0
	v_fma_f32 v86, |v90|, s64, 1.0
	v_fma_f32 v87, |v91|, s64, 1.0
	v_pk_mul_f32 v[106:107], v[90:91], v[90:91]
	v_rcp_f32_e32 v102, v86
	v_rcp_f32_e32 v103, v87
	v_mov_b64_e32 v[86:87], s[4:5]
	v_pk_mul_f32 v[106:107], v[106:107], s[76:77] op_sel_hi:[1,0]
	s_nop 0
	v_pk_fma_f32 v[104:105], v[102:103], s[66:67], v[86:87] op_sel_hi:[1,0,0]
	v_exp_f32_e32 v106, v106
	v_pk_fma_f32 v[104:105], v[102:103], v[104:105], s[70:71] op_sel_hi:[1,1,0]
	v_exp_f32_e32 v107, v107
	v_pk_fma_f32 v[104:105], v[102:103], v[104:105], s[72:73] op_sel_hi:[1,1,0]
	v_pk_mul_f32 v[92:93], v[92:93], v[0:1] op_sel_hi:[1,0]
	v_pk_fma_f32 v[104:105], v[102:103], v[104:105], s[74:75] op_sel_hi:[1,1,0]
	v_pk_mul_f32 v[88:89], v[88:89], v[0:1] op_sel_hi:[1,0]
	v_pk_mul_f32 v[102:103], v[102:103], v[104:105]
	v_pk_mul_f32 v[104:105], v[92:93], v[92:93]
	v_pk_mul_f32 v[102:103], v[106:107], v[102:103]
	v_pk_mul_f32 v[104:105], v[104:105], s[76:77] op_sel_hi:[1,0]
	v_max_f32_e32 v106, 0, v90
	v_max_f32_e32 v107, 0, v91
	v_fma_f32 v90, -|v90|, v102, v106
	v_fma_f32 v91, -|v91|, v103, v107
	v_exp_f32_e32 v104, v104
	s_nop 0
	s_nop 0
	s_nop 0
	v_exp_f32_e32 v105, v105
	s_nop 0
	s_nop 0
	v_fma_f32 v102, |v92|, s64, 1.0
	v_fma_f32 v103, |v93|, s64, 1.0
	s_nop 0
	v_rcp_f32_e32 v102, v102
	v_rcp_f32_e32 v103, v103
	v_lshl_add_u64 v[98:99], v[160:161], 1, v[98:99]
	v_pk_mul_f32 v[82:83], v[82:83], v[0:1] op_sel_hi:[1,0]
	v_pk_mul_f32 v[84:85], v[84:85], v[0:1] op_sel_hi:[1,0]
	v_pk_fma_f32 v[106:107], v[102:103], s[66:67], v[86:87] op_sel_hi:[1,0,0]
	v_pk_mul_f32 v[80:81], v[80:81], v[0:1] op_sel_hi:[1,0]
	v_pk_fma_f32 v[106:107], v[102:103], v[106:107], s[70:71] op_sel_hi:[1,1,0]
	s_nop 0
	v_pk_fma_f32 v[106:107], v[102:103], v[106:107], s[72:73] op_sel_hi:[1,1,0]
	s_nop 0
	v_pk_fma_f32 v[106:107], v[102:103], v[106:107], s[74:75] op_sel_hi:[1,1,0]
	s_nop 0
	v_pk_mul_f32 v[102:103], v[102:103], v[106:107]
	v_pk_mul_f32 v[106:107], v[100:101], v[100:101]
	v_pk_mul_f32 v[102:103], v[104:105], v[102:103]
	v_pk_mul_f32 v[106:107], v[106:107], s[76:77] op_sel_hi:[1,0]
	v_max_f32_e32 v104, 0, v92
	v_max_f32_e32 v105, 0, v93
	v_fma_f32 v92, -|v92|, v102, v104
	v_fma_f32 v93, -|v93|, v103, v105
	v_exp_f32_e32 v106, v106
	s_nop 0
	s_nop 0
	s_nop 0
	v_exp_f32_e32 v107, v107
	s_nop 0
	s_nop 0
	v_fma_f32 v102, |v100|, s64, 1.0
	v_fma_f32 v103, |v101|, s64, 1.0
	s_nop 0
	v_rcp_f32_e32 v102, v102
	v_rcp_f32_e32 v103, v103
	s_nop 0
	v_pk_fma_f32 v[104:105], v[102:103], s[66:67], v[86:87] op_sel_hi:[1,0,0]
	s_nop 0
	v_pk_fma_f32 v[104:105], v[102:103], v[104:105], s[70:71] op_sel_hi:[1,1,0]
	s_nop 0
	v_pk_fma_f32 v[104:105], v[102:103], v[104:105], s[72:73] op_sel_hi:[1,1,0]
	s_nop 0
	v_pk_fma_f32 v[104:105], v[102:103], v[104:105], s[74:75] op_sel_hi:[1,1,0]
	s_nop 0
	v_pk_mul_f32 v[102:103], v[102:103], v[104:105]
	v_pk_mul_f32 v[104:105], v[88:89], v[88:89]
	v_pk_mul_f32 v[102:103], v[106:107], v[102:103]
	v_pk_mul_f32 v[104:105], v[104:105], s[76:77] op_sel_hi:[1,0]
	v_max_f32_e32 v106, 0, v100
	v_max_f32_e32 v107, 0, v101
	v_fma_f32 v100, -|v100|, v102, v106
	v_fma_f32 v101, -|v101|, v103, v107
	v_exp_f32_e32 v104, v104
	s_nop 0
	s_nop 0
	s_nop 0
	v_exp_f32_e32 v105, v105
	s_nop 0
	s_nop 0
	v_fma_f32 v102, |v88|, s64, 1.0
	v_fma_f32 v103, |v89|, s64, 1.0
	s_nop 0
	v_rcp_f32_e32 v102, v102
	v_rcp_f32_e32 v103, v103
	s_nop 0
	v_pk_fma_f32 v[106:107], v[102:103], s[66:67], v[86:87] op_sel_hi:[1,0,0]
	s_nop 0
	v_pk_fma_f32 v[106:107], v[102:103], v[106:107], s[70:71] op_sel_hi:[1,1,0]
	s_nop 0
	v_pk_fma_f32 v[106:107], v[102:103], v[106:107], s[72:73] op_sel_hi:[1,1,0]
	s_nop 0
	v_pk_fma_f32 v[106:107], v[102:103], v[106:107], s[74:75] op_sel_hi:[1,1,0]
	s_nop 0
	v_pk_mul_f32 v[102:103], v[102:103], v[106:107]
	v_pk_mul_f32 v[106:107], v[82:83], v[82:83]
	v_pk_mul_f32 v[102:103], v[104:105], v[102:103]
	v_pk_mul_f32 v[106:107], v[106:107], s[76:77] op_sel_hi:[1,0]
	v_max_f32_e32 v104, 0, v88
	v_max_f32_e32 v105, 0, v89
	v_fma_f32 v88, -|v88|, v102, v104
	v_fma_f32 v89, -|v89|, v103, v105
	v_exp_f32_e32 v106, v106
	s_nop 0
	s_nop 0
	v_cvt_pk_bf16_f32 v102, v90, v91
	v_exp_f32_e32 v107, v107
	s_nop 0
	s_nop 0
	v_cvt_pk_bf16_f32 v103, v92, v93
	v_cvt_pk_bf16_f32 v104, v100, v101
	v_cvt_pk_bf16_f32 v105, v88, v89
	global_store_dwordx4 v[98:99], v[102:105], off
	s_nop 0
	s_nop 0
	v_pk_mul_f32 v[102:103], v[78:79], v[0:1] op_sel_hi:[1,0]
	s_nop 0
	s_nop 0
	v_fma_f32 v78, |v82|, s64, 1.0
	v_fma_f32 v79, |v83|, s64, 1.0
	s_nop 0
	v_rcp_f32_e32 v78, v78
	v_rcp_f32_e32 v79, v79
	s_nop 0
	v_pk_fma_f32 v[104:105], v[78:79], s[66:67], v[86:87] op_sel_hi:[1,0,0]
	s_nop 0
	v_pk_fma_f32 v[104:105], v[78:79], v[104:105], s[70:71] op_sel_hi:[1,1,0]
	s_nop 0
	v_pk_fma_f32 v[104:105], v[78:79], v[104:105], s[72:73] op_sel_hi:[1,1,0]
	s_nop 0
	v_pk_fma_f32 v[104:105], v[78:79], v[104:105], s[74:75] op_sel_hi:[1,1,0]
; __device__ __forceinline__ unsigned cvt_pk_bf16(float lo, float hi) { unsigned r; asm volatile("v_cvt_pk_bf16_f32 %0, %1, %2" : "=v"(r) : "v"(lo), "v"(hi)); return r; }
; __device__ __forceinline__ f32x2 gelu_pk(f32x2 v) {
;     const f32x2 av = __builtin_elementwise_abs(v), d = av * 0.2316418882f + 1.0f;
;     f32x2 t; t.x = __builtin_amdgcn_rcpf(d.x); t.y = __builtin_amdgcn_rcpf(d.y);
;     f32x2 q = t * 0.5307027145f + (-0.7265760135f); q = q * t + 0.7107068705f; q = q * t + (-0.142248368f); q = q * t + 0.127414796f; q = q * t;
;     const f32x2 s = (v * v) * (-0.72134752044f);
;     f32x2 e; e.x = __builtin_amdgcn_exp2f(s.x); e.y = __builtin_amdgcn_exp2f(s.y);
;     const f32x2 m = v * (q * e), r = v - m;
;     f32x2 o; o.x = v.x < 0.f ? m.x : r.x; o.y = v.y < 0.f ? m.y : r.y; return o;
; }
;     __device__ __forceinline__ void operator()(const f32x4 (&acc)[2][2][4][2], const Unit& u, int wr, int wc, int fr, int fq) const {
;     ...
;                 for (int bj = 0; bj < 2; ++bj) { f32x4 v0 = acc[ai][bj][m][0] * rs, v1 = acc[ai][bj][m][1] * rs;
;                     const f32x2 a = gelu_pk((f32x2){v0[0], v0[1]}), b = gelu_pk((f32x2){v0[2], v0[3]}), c = gelu_pk((f32x2){v1[0], v1[1]}), d = gelu_pk((f32x2){v1[2], v1[3]});
;                     s1 += ((a.x + a.y) + (b.x + b.y)) + ((c.x + c.y) + (d.x + d.y));
;                     s2 += ((a.x * a.x + a.y * a.y) + (b.x * b.x + b.y * b.y)) + ((c.x * c.x + c.y * c.y) + (d.x * d.x + d.y * d.y));
;                     u32x4 w; w.x = cvt_pk_bf16(a.x, a.y); w.y = cvt_pk_bf16(b.x, b.y); w.z = cvt_pk_bf16(c.x, c.y); w.w = cvt_pk_bf16(d.x, d.y);
;                     *(u32x4*)(rowp + bj * HALF) = w; }
;                 if (isv) { s1 += __shfl_xor(s1, 16); s1 += __shfl_xor(s1, 32); s2 += __shfl_xor(s2, 16); s2 += __shfl_xor(s2, 32);
;                     if (fq == 0) { const int rl = ai * HALF + wr * 64 + m * 16 + fr; part[rl * 4 + wc] = s1; part[1024 + rl * 4 + wc] = s2; } } }
	s_nop 0
	v_pk_mul_f32 v[78:79], v[78:79], v[104:105]
	v_pk_mul_f32 v[104:105], v[84:85], v[84:85]
	v_pk_mul_f32 v[78:79], v[106:107], v[78:79]
	v_pk_mul_f32 v[104:105], v[104:105], s[76:77] op_sel_hi:[1,0]
	v_max_f32_e32 v106, 0, v82
	v_max_f32_e32 v107, 0, v83
	v_fma_f32 v0, -|v82|, v78, v106
	v_fma_f32 v78, -|v83|, v79, v107
	s_nop 0
	s_nop 0
	s_nop 0
	s_nop 0
	v_fma_f32 v82, |v84|, s64, 1.0
	v_fma_f32 v83, |v85|, s64, 1.0
	s_nop 0
	v_rcp_f32_e32 v82, v82
	v_rcp_f32_e32 v83, v83
	v_exp_f32_e32 v104, v104
	v_exp_f32_e32 v105, v105
	s_nop 0
	v_pk_fma_f32 v[106:107], v[82:83], s[66:67], v[86:87] op_sel_hi:[1,0,0]
	s_nop 0
	v_pk_fma_f32 v[106:107], v[82:83], v[106:107], s[70:71] op_sel_hi:[1,1,0]
	s_nop 0
	v_pk_fma_f32 v[106:107], v[82:83], v[106:107], s[72:73] op_sel_hi:[1,1,0]
	s_nop 0
	v_pk_fma_f32 v[106:107], v[82:83], v[106:107], s[74:75] op_sel_hi:[1,1,0]
	s_nop 0
	v_pk_mul_f32 v[82:83], v[82:83], v[106:107]
	v_pk_mul_f32 v[106:107], v[102:103], v[102:103]
	v_pk_mul_f32 v[82:83], v[104:105], v[82:83]
	v_pk_mul_f32 v[106:107], v[106:107], s[76:77] op_sel_hi:[1,0]
	v_max_f32_e32 v104, 0, v84
	v_max_f32_e32 v105, 0, v85
	v_fma_f32 v79, -|v84|, v82, v104
	v_fma_f32 v82, -|v85|, v83, v105
	s_nop 0
	s_nop 0
	s_nop 0
	s_nop 0
	v_fma_f32 v84, |v102|, s64, 1.0
	v_fma_f32 v85, |v103|, s64, 1.0
	s_nop 0
	v_rcp_f32_e32 v84, v84
	v_rcp_f32_e32 v85, v85
	v_exp_f32_e32 v106, v106
	v_exp_f32_e32 v107, v107
	s_nop 0
	v_pk_fma_f32 v[104:105], v[84:85], s[66:67], v[86:87] op_sel_hi:[1,0,0]
	s_nop 0
	v_pk_fma_f32 v[104:105], v[84:85], v[104:105], s[70:71] op_sel_hi:[1,1,0]
	s_nop 0
	v_pk_fma_f32 v[104:105], v[84:85], v[104:105], s[72:73] op_sel_hi:[1,1,0]
	s_nop 0
	v_pk_fma_f32 v[104:105], v[84:85], v[104:105], s[74:75] op_sel_hi:[1,1,0]
	s_nop 0
	v_pk_mul_f32 v[84:85], v[84:85], v[104:105]
	v_pk_mul_f32 v[104:105], v[80:81], v[80:81]
	v_pk_mul_f32 v[84:85], v[106:107], v[84:85]
	s_nop 0
	v_max_f32_e32 v106, 0, v102
	v_max_f32_e32 v107, 0, v103
	v_fma_f32 v83, -|v102|, v84, v106
	v_fma_f32 v84, -|v103|, v85, v107
	s_nop 0
	s_nop 0
	s_nop 0
	s_nop 0
	v_fma_f32 v102, |v80|, s64, 1.0
	v_fma_f32 v103, |v81|, s64, 1.0
	s_nop 0
	v_rcp_f32_e32 v102, v102
	v_rcp_f32_e32 v103, v103
	s_nop 0
	v_pk_fma_f32 v[86:87], v[102:103], s[66:67], v[86:87] op_sel_hi:[1,0,0]
	s_nop 0
	v_pk_fma_f32 v[86:87], v[102:103], v[86:87], s[70:71] op_sel_hi:[1,1,0]
	s_nop 0
	v_pk_fma_f32 v[86:87], v[102:103], v[86:87], s[72:73] op_sel_hi:[1,1,0]
	s_nop 0
	v_pk_fma_f32 v[86:87], v[102:103], v[86:87], s[74:75] op_sel_hi:[1,1,0]
	s_nop 0
	v_pk_mul_f32 v[86:87], v[102:103], v[86:87]
	v_pk_mul_f32 v[102:103], v[104:105], s[76:77] op_sel_hi:[1,0]
	s_nop 0
	v_exp_f32_e32 v102, v102
	v_exp_f32_e32 v103, v103
	s_nop 0
	v_pk_mul_f32 v[86:87], v[102:103], v[86:87]
	s_nop 0
	v_max_f32_e32 v102, 0, v80
	v_max_f32_e32 v103, 0, v81
	v_fma_f32 v80, -|v80|, v86, v102
	v_fma_f32 v81, -|v81|, v87, v103
	s_nop 0
	s_nop 0
	s_nop 0
	v_cvt_pk_bf16_f32 v102, v0, v78
	s_nop 1
	s_nop 0
	s_and_b64 vcc, exec, s[10:11]
	v_cvt_pk_bf16_f32 v103, v79, v82
	v_cvt_pk_bf16_f32 v104, v83, v84
	v_cvt_pk_bf16_f32 v105, v80, v81
	global_store_dwordx4 v[98:99], v[102:105], off offset:256
	s_cbranch_vccnz .LBB0_368
	v_mul_f32_e32 v85, v91, v91
	v_mul_f32_e32 v86, v93, v93
	v_fmac_f32_e32 v85, v90, v90
	v_fmac_f32_e32 v86, v92, v92
	v_add_f32_e32 v85, v85, v86
	v_mul_f32_e32 v86, v101, v101
	v_mul_f32_e32 v87, v89, v89
	v_fmac_f32_e32 v86, v100, v100
	v_fmac_f32_e32 v87, v88, v88
	v_add_f32_e32 v86, v86, v87
	v_add_f32_e32 v85, v85, v86
	v_mul_f32_e32 v86, v78, v78
	v_fmac_f32_e32 v86, v0, v0
	v_mul_f32_e32 v87, v82, v82
	v_add_f32_e32 v0, v0, v78
	v_add_f32_e32 v78, v79, v82
	v_fmac_f32_e32 v87, v79, v79
	v_add_f32_e32 v90, v90, v91
	v_add_f32_e32 v91, v92, v93
	v_add_f32_e32 v0, v0, v78
	v_add_f32_e32 v78, v83, v84
	v_add_f32_e32 v79, v80, v81
	v_add_f32_e32 v90, v90, v91
	v_add_f32_e32 v91, v100, v101
	v_add_f32_e32 v88, v88, v89
	v_add_f32_e32 v78, v78, v79
	v_and_b32_e32 v79, 64, v226
	v_add_f32_e32 v88, v91, v88
	v_add_f32_e32 v0, v0, v78
	v_xor_b32_e32 v78, 16, v226
	v_add_u32_e32 v79, 64, v79
	v_add_f32_e32 v88, v90, v88
	v_cmp_lt_i32_e32 vcc, v78, v79
	v_add_f32_e32 v86, v86, v87
	v_mul_f32_e32 v87, v84, v84
	v_mul_f32_e32 v98, v81, v81
	v_add_f32_e32 v88, 0, v88
	v_cndmask_b32_e32 v78, v226, v78, vcc
	v_fmac_f32_e32 v87, v83, v83
	v_add_f32_e32 v0, v0, v88
	v_lshlrev_b32_e32 v78, 2, v78
	v_fmac_f32_e32 v98, v80, v80
	v_mov_b32_e32 v81, v0
	s_nop 1
	v_permlane16_swap_b32_e32 v81, v0
	v_add_f32_e32 v80, v87, v98
	v_add_f32_e32 v80, v86, v80
	v_add_f32_e32 v80, v85, v80
	v_mov_b32_e32 v82, v80
	s_nop 1
	v_permlane16_swap_b32_e32 v82, v80
	s_waitcnt lgkmcnt(0)
	v_add_f32_e32 v0, v0, v81
	v_xor_b32_e32 v81, 32, v226
	v_cmp_lt_i32_e32 vcc, v81, v79
	v_add_f32_e32 v79, v80, v82
	s_nop 0
	v_cndmask_b32_e32 v78, v226, v81, vcc
	v_lshlrev_b32_e32 v81, 2, v78
	v_mov_b32_e32 v78, v0
	s_nop 1
	v_permlane32_swap_b32_e32 v78, v0
	v_mov_b32_e32 v80, v79
	s_nop 1
	v_permlane32_swap_b32_e32 v80, v79
	s_and_saveexec_b64 s[4:5], s[6:7]
	s_cbranch_execz .LBB0_367
	s_waitcnt lgkmcnt(0)
	v_add_f32_e32 v79, v79, v80
	v_add_f32_e32 v0, v0, v78
	ds_write2st64_b32 v186, v0, v79 offset0:3 offset1:19

; __device__ __forceinline__ unsigned cvt_pk_bf16(float lo, float hi) { unsigned r; asm volatile("v_cvt_pk_bf16_f32 %0, %1, %2" : "=v"(r) : "v"(lo), "v"(hi)); return r; }
; __device__ __forceinline__ f32x2 gelu_pk(f32x2 v) {
;     const f32x2 av = __builtin_elementwise_abs(v), d = av * 0.2316418882f + 1.0f;
;     f32x2 t; t.x = __builtin_amdgcn_rcpf(d.x); t.y = __builtin_amdgcn_rcpf(d.y);
;     f32x2 q = t * 0.5307027145f + (-0.7265760135f); q = q * t + 0.7107068705f; q = q * t + (-0.142248368f); q = q * t + 0.127414796f; q = q * t;
;     const f32x2 s = (v * v) * (-0.72134752044f);
;     f32x2 e; e.x = __builtin_amdgcn_exp2f(s.x); e.y = __builtin_amdgcn_exp2f(s.y);
;     const f32x2 m = v * (q * e), r = v - m;
;     f32x2 o; o.x = v.x < 0.f ? m.x : r.x; o.y = v.y < 0.f ? m.y : r.y; return o;
;     __device__ __forceinline__ void operator()(const f32x4 (&acc)[2][2][4][2], const Unit& u, int wr, int wc, int fr, int fq) const {
;     ...
;             for (int m = 0; m < 4; ++m) { const int row = row0 + ai * HALF + m * 16; const float rs = rsv[ai][m]; bf16_t* rowp = O + (size_t)row * ldc + col0; float s1 = 0.f, s2 = 0.f;
; #pragma unroll
;                 for (int bj = 0; bj < 2; ++bj) { f32x4 v0 = acc[ai][bj][m][0] * rs, v1 = acc[ai][bj][m][1] * rs;
;                     const f32x2 a = gelu_pk((f32x2){v0[0], v0[1]}), b = gelu_pk((f32x2){v0[2], v0[3]}), c = gelu_pk((f32x2){v1[0], v1[1]}), d = gelu_pk((f32x2){v1[2], v1[3]});
;                     s1 += ((a.x + a.y) + (b.x + b.y)) + ((c.x + c.y) + (d.x + d.y));
;                     s2 += ((a.x * a.x + a.y * a.y) + (b.x * b.x + b.y * b.y)) + ((c.x * c.x + c.y * c.y) + (d.x * d.x + d.y * d.y));
;                     u32x4 w; w.x = cvt_pk_bf16(a.x, a.y); w.y = cvt_pk_bf16(b.x, b.y); w.z = cvt_pk_bf16(c.x, c.y); w.w = cvt_pk_bf16(d.x, d.y);
;                     *(u32x4*)(rowp + bj * HALF) = w; }
.LBB0_368:
	v_add_f32_e32 v0, v94, v95
	s_waitcnt lgkmcnt(0)
	v_add_f32_e32 v78, v96, v97
	v_add_f32_e32 v0, v0, v78
	v_fmamk_f32 v0, v0, 0x3a800000, v224
	v_rsq_f32_e32 v0, v0
	s_mov_b32 s4, 0xbf3a00e3
	v_lshlrev_b64 v[78:79], 12, v[168:169]
	v_lshl_add_u64 v[78:79], s[20:21], 0, v[78:79]
	v_pk_mul_f32 v[70:71], v[70:71], v[0:1] op_sel_hi:[1,0]
	v_pk_mul_f32 v[80:81], v[66:67], v[0:1] op_sel_hi:[1,0]
	s_nop 0
	s_nop 0
	v_fma_f32 v66, |v70|, s64, 1.0
	v_fma_f32 v67, |v71|, s64, 1.0
	v_pk_mul_f32 v[86:87], v[70:71], v[70:71]
	v_rcp_f32_e32 v82, v66
	v_rcp_f32_e32 v83, v67
	v_mov_b64_e32 v[66:67], s[4:5]
	v_pk_mul_f32 v[86:87], v[86:87], s[76:77] op_sel_hi:[1,0]
	s_nop 0
	v_pk_fma_f32 v[84:85], v[82:83], s[66:67], v[66:67] op_sel_hi:[1,0,0]
	v_exp_f32_e32 v86, v86
	v_pk_fma_f32 v[84:85], v[82:83], v[84:85], s[70:71] op_sel_hi:[1,1,0]
	v_exp_f32_e32 v87, v87
	v_pk_fma_f32 v[84:85], v[82:83], v[84:85], s[72:73] op_sel_hi:[1,1,0]
	v_pk_mul_f32 v[72:73], v[72:73], v[0:1] op_sel_hi:[1,0]
	v_pk_fma_f32 v[84:85], v[82:83], v[84:85], s[74:75] op_sel_hi:[1,1,0]
	v_pk_mul_f32 v[68:69], v[68:69], v[0:1] op_sel_hi:[1,0]
	v_pk_mul_f32 v[82:83], v[82:83], v[84:85]
	v_pk_mul_f32 v[84:85], v[72:73], v[72:73]
	v_pk_mul_f32 v[82:83], v[86:87], v[82:83]
	v_pk_mul_f32 v[84:85], v[84:85], s[76:77] op_sel_hi:[1,0]
	v_max_f32_e32 v86, 0, v70
	v_max_f32_e32 v87, 0, v71
	v_fma_f32 v70, -|v70|, v82, v86
	v_fma_f32 v71, -|v71|, v83, v87
	v_exp_f32_e32 v84, v84
	s_nop 0
	s_nop 0
	s_nop 0
	v_exp_f32_e32 v85, v85
	s_nop 0
	s_nop 0
	v_fma_f32 v82, |v72|, s64, 1.0
	v_fma_f32 v83, |v73|, s64, 1.0
	s_nop 0
	v_rcp_f32_e32 v82, v82
	v_rcp_f32_e32 v83, v83
	v_lshl_add_u64 v[78:79], v[160:161], 1, v[78:79]
	v_pk_mul_f32 v[62:63], v[62:63], v[0:1] op_sel_hi:[1,0]
	v_pk_mul_f32 v[64:65], v[64:65], v[0:1] op_sel_hi:[1,0]
	v_pk_fma_f32 v[86:87], v[82:83], s[66:67], v[66:67] op_sel_hi:[1,0,0]
	v_pk_mul_f32 v[60:61], v[60:61], v[0:1] op_sel_hi:[1,0]
	v_pk_fma_f32 v[86:87], v[82:83], v[86:87], s[70:71] op_sel_hi:[1,1,0]
	s_nop 0
	v_pk_fma_f32 v[86:87], v[82:83], v[86:87], s[72:73] op_sel_hi:[1,1,0]
	s_nop 0
	v_pk_fma_f32 v[86:87], v[82:83], v[86:87], s[74:75] op_sel_hi:[1,1,0]
	s_nop 0
	v_pk_mul_f32 v[82:83], v[82:83], v[86:87]
	v_pk_mul_f32 v[86:87], v[80:81], v[80:81]
	v_pk_mul_f32 v[82:83], v[84:85], v[82:83]
	v_pk_mul_f32 v[86:87], v[86:87], s[76:77] op_sel_hi:[1,0]
	v_max_f32_e32 v84, 0, v72
	v_max_f32_e32 v85, 0, v73
	v_fma_f32 v72, -|v72|, v82, v84
	v_fma_f32 v73, -|v73|, v83, v85
	v_exp_f32_e32 v86, v86
	s_nop 0
	s_nop 0
	s_nop 0
	v_exp_f32_e32 v87, v87
	s_nop 0
	s_nop 0
	v_fma_f32 v82, |v80|, s64, 1.0
	v_fma_f32 v83, |v81|, s64, 1.0
	s_nop 0
	v_rcp_f32_e32 v82, v82
	v_rcp_f32_e32 v83, v83
	s_nop 0
	v_pk_fma_f32 v[84:85], v[82:83], s[66:67], v[66:67] op_sel_hi:[1,0,0]
	s_nop 0
	v_pk_fma_f32 v[84:85], v[82:83], v[84:85], s[70:71] op_sel_hi:[1,1,0]
	s_nop 0
	v_pk_fma_f32 v[84:85], v[82:83], v[84:85], s[72:73] op_sel_hi:[1,1,0]
	s_nop 0
	v_pk_fma_f32 v[84:85], v[82:83], v[84:85], s[74:75] op_sel_hi:[1,1,0]
	s_nop 0
	v_pk_mul_f32 v[82:83], v[82:83], v[84:85]
	v_pk_mul_f32 v[84:85], v[68:69], v[68:69]
	v_pk_mul_f32 v[82:83], v[86:87], v[82:83]
	v_pk_mul_f32 v[84:85], v[84:85], s[76:77] op_sel_hi:[1,0]
	v_max_f32_e32 v86, 0, v80
	v_max_f32_e32 v87, 0, v81
	v_fma_f32 v80, -|v80|, v82, v86
	v_fma_f32 v81, -|v81|, v83, v87
	v_exp_f32_e32 v84, v84
	s_nop 0
	s_nop 0
	s_nop 0
	v_exp_f32_e32 v85, v85
	s_nop 0
	s_nop 0
	v_fma_f32 v82, |v68|, s64, 1.0
	v_fma_f32 v83, |v69|, s64, 1.0
	s_nop 0
	v_rcp_f32_e32 v82, v82
	v_rcp_f32_e32 v83, v83
	s_nop 0
	v_pk_fma_f32 v[86:87], v[82:83], s[66:67], v[66:67] op_sel_hi:[1,0,0]
	s_nop 0
	v_pk_fma_f32 v[86:87], v[82:83], v[86:87], s[70:71] op_sel_hi:[1,1,0]
	s_nop 0
	v_pk_fma_f32 v[86:87], v[82:83], v[86:87], s[72:73] op_sel_hi:[1,1,0]
	s_nop 0
	v_pk_fma_f32 v[86:87], v[82:83], v[86:87], s[74:75] op_sel_hi:[1,1,0]
	s_nop 0
	v_pk_mul_f32 v[82:83], v[82:83], v[86:87]
	v_pk_mul_f32 v[86:87], v[62:63], v[62:63]
	v_pk_mul_f32 v[82:83], v[84:85], v[82:83]
	v_pk_mul_f32 v[86:87], v[86:87], s[76:77] op_sel_hi:[1,0]
	v_max_f32_e32 v84, 0, v68
	v_max_f32_e32 v85, 0, v69
	v_fma_f32 v68, -|v68|, v82, v84
	v_fma_f32 v69, -|v69|, v83, v85
	v_exp_f32_e32 v86, v86
	s_nop 0
	s_nop 0
	v_cvt_pk_bf16_f32 v82, v70, v71
	v_exp_f32_e32 v87, v87
	s_nop 0
	s_nop 0
	v_cvt_pk_bf16_f32 v83, v72, v73
	v_cvt_pk_bf16_f32 v84, v80, v81
	v_cvt_pk_bf16_f32 v85, v68, v69
	global_store_dwordx4 v[78:79], v[82:85], off
	s_nop 0
	s_nop 0
	v_pk_mul_f32 v[82:83], v[58:59], v[0:1] op_sel_hi:[1,0]
	s_nop 0
	s_nop 0
	v_fma_f32 v58, |v62|, s64, 1.0
	v_fma_f32 v59, |v63|, s64, 1.0
	s_nop 0
	v_rcp_f32_e32 v58, v58
	v_rcp_f32_e32 v59, v59
	s_nop 0
	v_pk_fma_f32 v[84:85], v[58:59], s[66:67], v[66:67] op_sel_hi:[1,0,0]
	s_nop 0
	v_pk_fma_f32 v[84:85], v[58:59], v[84:85], s[70:71] op_sel_hi:[1,1,0]
	s_nop 0
	v_pk_fma_f32 v[84:85], v[58:59], v[84:85], s[72:73] op_sel_hi:[1,1,0]
	s_nop 0
	v_pk_fma_f32 v[84:85], v[58:59], v[84:85], s[74:75] op_sel_hi:[1,1,0]
	s_nop 0
	v_pk_mul_f32 v[58:59], v[58:59], v[84:85]
; __device__ __forceinline__ unsigned cvt_pk_bf16(float lo, float hi) { unsigned r; asm volatile("v_cvt_pk_bf16_f32 %0, %1, %2" : "=v"(r) : "v"(lo), "v"(hi)); return r; }
; __device__ __forceinline__ f32x2 gelu_pk(f32x2 v) {
;     const f32x2 av = __builtin_elementwise_abs(v), d = av * 0.2316418882f + 1.0f;
;     f32x2 t; t.x = __builtin_amdgcn_rcpf(d.x); t.y = __builtin_amdgcn_rcpf(d.y);
;     f32x2 q = t * 0.5307027145f + (-0.7265760135f); q = q * t + 0.7107068705f; q = q * t + (-0.142248368f); q = q * t + 0.127414796f; q = q * t;
;     const f32x2 s = (v * v) * (-0.72134752044f);
;     f32x2 e; e.x = __builtin_amdgcn_exp2f(s.x); e.y = __builtin_amdgcn_exp2f(s.y);
;     const f32x2 m = v * (q * e), r = v - m;
;     f32x2 o; o.x = v.x < 0.f ? m.x : r.x; o.y = v.y < 0.f ? m.y : r.y; return o;
;     __device__ __forceinline__ void operator()(const f32x4 (&acc)[2][2][4][2], const Unit& u, int wr, int wc, int fr, int fq) const {
;     ...
;                 for (int bj = 0; bj < 2; ++bj) { f32x4 v0 = acc[ai][bj][m][0] * rs, v1 = acc[ai][bj][m][1] * rs;
;                     const f32x2 a = gelu_pk((f32x2){v0[0], v0[1]}), b = gelu_pk((f32x2){v0[2], v0[3]}), c = gelu_pk((f32x2){v1[0], v1[1]}), d = gelu_pk((f32x2){v1[2], v1[3]});
;                     s1 += ((a.x + a.y) + (b.x + b.y)) + ((c.x + c.y) + (d.x + d.y));
;                     s2 += ((a.x * a.x + a.y * a.y) + (b.x * b.x + b.y * b.y)) + ((c.x * c.x + c.y * c.y) + (d.x * d.x + d.y * d.y));
;                     u32x4 w; w.x = cvt_pk_bf16(a.x, a.y); w.y = cvt_pk_bf16(b.x, b.y); w.z = cvt_pk_bf16(c.x, c.y); w.w = cvt_pk_bf16(d.x, d.y);
;                     *(u32x4*)(rowp + bj * HALF) = w; }
;                 if (isv) { s1 += __shfl_xor(s1, 16); s1 += __shfl_xor(s1, 32); s2 += __shfl_xor(s2, 16); s2 += __shfl_xor(s2, 32);
;                     if (fq == 0) { const int rl = ai * HALF + wr * 64 + m * 16 + fr; part[rl * 4 + wc] = s1; part[1024 + rl * 4 + wc] = s2; } } }
	v_pk_mul_f32 v[84:85], v[64:65], v[64:65]
	v_pk_mul_f32 v[58:59], v[86:87], v[58:59]
	v_pk_mul_f32 v[84:85], v[84:85], s[76:77] op_sel_hi:[1,0]
	v_max_f32_e32 v86, 0, v62
	v_max_f32_e32 v87, 0, v63
	v_fma_f32 v0, -|v62|, v58, v86
	v_fma_f32 v58, -|v63|, v59, v87
	s_nop 0
	s_nop 0
	s_nop 0
	s_nop 0
	v_fma_f32 v62, |v64|, s64, 1.0
	v_fma_f32 v63, |v65|, s64, 1.0
	s_nop 0
	v_rcp_f32_e32 v62, v62
	v_rcp_f32_e32 v63, v63
	v_exp_f32_e32 v84, v84
	v_exp_f32_e32 v85, v85
	s_nop 0
	v_pk_fma_f32 v[86:87], v[62:63], s[66:67], v[66:67] op_sel_hi:[1,0,0]
	s_nop 0
	v_pk_fma_f32 v[86:87], v[62:63], v[86:87], s[70:71] op_sel_hi:[1,1,0]
	s_nop 0
	v_pk_fma_f32 v[86:87], v[62:63], v[86:87], s[72:73] op_sel_hi:[1,1,0]
	s_nop 0
	v_pk_fma_f32 v[86:87], v[62:63], v[86:87], s[74:75] op_sel_hi:[1,1,0]
	s_nop 0
	v_pk_mul_f32 v[62:63], v[62:63], v[86:87]
	v_pk_mul_f32 v[86:87], v[82:83], v[82:83]
	v_pk_mul_f32 v[62:63], v[84:85], v[62:63]
	v_pk_mul_f32 v[86:87], v[86:87], s[76:77] op_sel_hi:[1,0]
	v_max_f32_e32 v84, 0, v64
	v_max_f32_e32 v85, 0, v65
	v_fma_f32 v59, -|v64|, v62, v84
	v_fma_f32 v62, -|v65|, v63, v85
	s_nop 0
	s_nop 0
	s_nop 0
	s_nop 0
	v_fma_f32 v64, |v82|, s64, 1.0
	v_fma_f32 v65, |v83|, s64, 1.0
	s_nop 0
	v_rcp_f32_e32 v64, v64
	v_rcp_f32_e32 v65, v65
	v_exp_f32_e32 v86, v86
	v_exp_f32_e32 v87, v87
	s_nop 0
	v_pk_fma_f32 v[84:85], v[64:65], s[66:67], v[66:67] op_sel_hi:[1,0,0]
	s_nop 0
	v_pk_fma_f32 v[84:85], v[64:65], v[84:85], s[70:71] op_sel_hi:[1,1,0]
	s_nop 0
	v_pk_fma_f32 v[84:85], v[64:65], v[84:85], s[72:73] op_sel_hi:[1,1,0]
	s_nop 0
	v_pk_fma_f32 v[84:85], v[64:65], v[84:85], s[74:75] op_sel_hi:[1,1,0]
	s_nop 0
	v_pk_mul_f32 v[64:65], v[64:65], v[84:85]
	v_pk_mul_f32 v[84:85], v[60:61], v[60:61]
	v_pk_mul_f32 v[64:65], v[86:87], v[64:65]
	s_nop 0
	v_max_f32_e32 v86, 0, v82
	v_max_f32_e32 v87, 0, v83
	v_fma_f32 v63, -|v82|, v64, v86
	v_fma_f32 v64, -|v83|, v65, v87
	s_nop 0
	s_nop 0
	s_nop 0
	s_nop 0
	v_fma_f32 v82, |v60|, s64, 1.0
	v_fma_f32 v83, |v61|, s64, 1.0
	s_nop 0
	v_rcp_f32_e32 v82, v82
	v_rcp_f32_e32 v83, v83
	s_nop 0
	v_pk_fma_f32 v[66:67], v[82:83], s[66:67], v[66:67] op_sel_hi:[1,0,0]
	s_nop 0
	v_pk_fma_f32 v[66:67], v[82:83], v[66:67], s[70:71] op_sel_hi:[1,1,0]
	s_nop 0
	v_pk_fma_f32 v[66:67], v[82:83], v[66:67], s[72:73] op_sel_hi:[1,1,0]
	s_nop 0
	v_pk_fma_f32 v[66:67], v[82:83], v[66:67], s[74:75] op_sel_hi:[1,1,0]
	s_nop 0
	v_pk_mul_f32 v[66:67], v[82:83], v[66:67]
	v_pk_mul_f32 v[82:83], v[84:85], s[76:77] op_sel_hi:[1,0]
	s_nop 0
	v_exp_f32_e32 v82, v82
	v_exp_f32_e32 v83, v83
	s_nop 0
	v_pk_mul_f32 v[66:67], v[82:83], v[66:67]
	s_nop 0
	v_max_f32_e32 v82, 0, v60
	v_max_f32_e32 v83, 0, v61
	v_fma_f32 v60, -|v60|, v66, v82
	v_fma_f32 v61, -|v61|, v67, v83
	s_nop 0
	s_nop 0
	s_nop 0
	v_cvt_pk_bf16_f32 v82, v0, v58
	s_nop 1
	s_nop 0
	s_and_b64 vcc, exec, s[10:11]
	v_cvt_pk_bf16_f32 v83, v59, v62
	v_cvt_pk_bf16_f32 v84, v63, v64
	v_cvt_pk_bf16_f32 v85, v60, v61
	global_store_dwordx4 v[78:79], v[82:85], off offset:256
	s_cbranch_vccnz .LBB0_372
	v_mul_f32_e32 v65, v71, v71
	v_mul_f32_e32 v66, v73, v73
	v_fmac_f32_e32 v65, v70, v70
	v_fmac_f32_e32 v66, v72, v72
	v_add_f32_e32 v65, v65, v66
	v_mul_f32_e32 v66, v81, v81
	v_mul_f32_e32 v67, v69, v69
	v_fmac_f32_e32 v66, v80, v80
	v_fmac_f32_e32 v67, v68, v68
	v_add_f32_e32 v66, v66, v67
	v_add_f32_e32 v65, v65, v66
	v_mul_f32_e32 v66, v58, v58
	v_fmac_f32_e32 v66, v0, v0
	v_mul_f32_e32 v67, v62, v62
	v_add_f32_e32 v0, v0, v58
	v_add_f32_e32 v58, v59, v62
	v_fmac_f32_e32 v67, v59, v59
	v_add_f32_e32 v70, v70, v71
	v_add_f32_e32 v71, v72, v73
	v_add_f32_e32 v0, v0, v58
	v_add_f32_e32 v58, v63, v64
	v_add_f32_e32 v59, v60, v61
	v_add_f32_e32 v70, v70, v71
	v_add_f32_e32 v71, v80, v81
	v_add_f32_e32 v68, v68, v69
	v_add_f32_e32 v58, v58, v59
	v_and_b32_e32 v59, 64, v226
	v_add_f32_e32 v68, v71, v68
	v_add_f32_e32 v0, v0, v58
	v_xor_b32_e32 v58, 16, v226
	v_add_u32_e32 v59, 64, v59
	v_add_f32_e32 v68, v70, v68
	v_cmp_lt_i32_e32 vcc, v58, v59
	v_add_f32_e32 v66, v66, v67
	v_mul_f32_e32 v67, v64, v64
	v_mul_f32_e32 v78, v61, v61
	v_add_f32_e32 v68, 0, v68
	v_cndmask_b32_e32 v58, v226, v58, vcc
	v_fmac_f32_e32 v67, v63, v63
	v_add_f32_e32 v0, v0, v68
	v_lshlrev_b32_e32 v58, 2, v58
	v_fmac_f32_e32 v78, v60, v60
	v_mov_b32_e32 v61, v0
	s_nop 1
	v_permlane16_swap_b32_e32 v61, v0
	v_add_f32_e32 v60, v67, v78
	v_add_f32_e32 v60, v66, v60
	v_add_f32_e32 v60, v65, v60
	v_mov_b32_e32 v62, v60
	s_nop 1
	v_permlane16_swap_b32_e32 v62, v60
	s_waitcnt lgkmcnt(0)
	v_add_f32_e32 v0, v0, v61
	v_xor_b32_e32 v61, 32, v226
	v_cmp_lt_i32_e32 vcc, v61, v59
	v_add_f32_e32 v59, v60, v62
	s_nop 0
	v_cndmask_b32_e32 v58, v226, v61, vcc
	v_lshlrev_b32_e32 v61, 2, v58
	v_mov_b32_e32 v58, v0
	s_nop 1
	v_permlane32_swap_b32_e32 v58, v0
	v_mov_b32_e32 v60, v59
	s_nop 1
	v_permlane32_swap_b32_e32 v60, v59
	s_and_saveexec_b64 s[4:5], s[6:7]
	s_cbranch_execz .LBB0_371
	s_waitcnt lgkmcnt(0)
	v_add_f32_e32 v59, v59, v60
	v_add_f32_e32 v0, v0, v58
	ds_write2st64_b32 v186, v0, v59 offset0:8 offset1:24

; __device__ __forceinline__ unsigned cvt_pk_bf16(float lo, float hi) { unsigned r; asm volatile("v_cvt_pk_bf16_f32 %0, %1, %2" : "=v"(r) : "v"(lo), "v"(hi)); return r; }
; __device__ __forceinline__ f32x2 gelu_pk(f32x2 v) {
;     const f32x2 av = __builtin_elementwise_abs(v), d = av * 0.2316418882f + 1.0f;
;     f32x2 t; t.x = __builtin_amdgcn_rcpf(d.x); t.y = __builtin_amdgcn_rcpf(d.y);
;     f32x2 q = t * 0.5307027145f + (-0.7265760135f); q = q * t + 0.7107068705f; q = q * t + (-0.142248368f); q = q * t + 0.127414796f; q = q * t;
;     const f32x2 s = (v * v) * (-0.72134752044f);
;     f32x2 e; e.x = __builtin_amdgcn_exp2f(s.x); e.y = __builtin_amdgcn_exp2f(s.y);
;     const f32x2 m = v * (q * e), r = v - m;
;     f32x2 o; o.x = v.x < 0.f ? m.x : r.x; o.y = v.y < 0.f ? m.y : r.y; return o;
;     __device__ __forceinline__ void operator()(const f32x4 (&acc)[2][2][4][2], const Unit& u, int wr, int wc, int fr, int fq) const {
;     ...
;             for (int m = 0; m < 4; ++m) { const int row = row0 + ai * HALF + m * 16; const float rs = rsv[ai][m]; bf16_t* rowp = O + (size_t)row * ldc + col0; float s1 = 0.f, s2 = 0.f;
; #pragma unroll
;                 for (int bj = 0; bj < 2; ++bj) { f32x4 v0 = acc[ai][bj][m][0] * rs, v1 = acc[ai][bj][m][1] * rs;
;                     const f32x2 a = gelu_pk((f32x2){v0[0], v0[1]}), b = gelu_pk((f32x2){v0[2], v0[3]}), c = gelu_pk((f32x2){v1[0], v1[1]}), d = gelu_pk((f32x2){v1[2], v1[3]});
;                     s1 += ((a.x + a.y) + (b.x + b.y)) + ((c.x + c.y) + (d.x + d.y));
;                     s2 += ((a.x * a.x + a.y * a.y) + (b.x * b.x + b.y * b.y)) + ((c.x * c.x + c.y * c.y) + (d.x * d.x + d.y * d.y));
;                     u32x4 w; w.x = cvt_pk_bf16(a.x, a.y); w.y = cvt_pk_bf16(b.x, b.y); w.z = cvt_pk_bf16(c.x, c.y); w.w = cvt_pk_bf16(d.x, d.y);
;                     *(u32x4*)(rowp + bj * HALF) = w; }
.LBB0_372:
	v_add_f32_e32 v0, v74, v75
	s_waitcnt lgkmcnt(0)
	v_add_f32_e32 v58, v76, v77
	v_add_f32_e32 v0, v0, v58
	v_fmamk_f32 v0, v0, 0x3a800000, v224
	v_rsq_f32_e32 v0, v0
	s_mov_b32 s4, 0xbf3a00e3
	v_lshlrev_b64 v[58:59], 12, v[166:167]
	v_lshl_add_u64 v[58:59], s[20:21], 0, v[58:59]
	v_pk_mul_f32 v[50:51], v[50:51], v[0:1] op_sel_hi:[1,0]
	v_pk_mul_f32 v[60:61], v[46:47], v[0:1] op_sel_hi:[1,0]
	s_nop 0
	s_nop 0
	v_fma_f32 v46, |v50|, s64, 1.0
	v_fma_f32 v47, |v51|, s64, 1.0
	v_pk_mul_f32 v[66:67], v[50:51], v[50:51]
	v_rcp_f32_e32 v62, v46
	v_rcp_f32_e32 v63, v47
	v_mov_b64_e32 v[46:47], s[4:5]
	v_pk_mul_f32 v[66:67], v[66:67], s[76:77] op_sel_hi:[1,0]
	s_nop 0
	v_pk_fma_f32 v[64:65], v[62:63], s[66:67], v[46:47] op_sel_hi:[1,0,0]
	v_exp_f32_e32 v66, v66
	v_pk_fma_f32 v[64:65], v[62:63], v[64:65], s[70:71] op_sel_hi:[1,1,0]
	v_exp_f32_e32 v67, v67
	v_pk_fma_f32 v[64:65], v[62:63], v[64:65], s[72:73] op_sel_hi:[1,1,0]
	v_pk_mul_f32 v[52:53], v[52:53], v[0:1] op_sel_hi:[1,0]
	v_pk_fma_f32 v[64:65], v[62:63], v[64:65], s[74:75] op_sel_hi:[1,1,0]
	v_pk_mul_f32 v[48:49], v[48:49], v[0:1] op_sel_hi:[1,0]
	v_pk_mul_f32 v[62:63], v[62:63], v[64:65]
	v_pk_mul_f32 v[64:65], v[52:53], v[52:53]
	v_pk_mul_f32 v[62:63], v[66:67], v[62:63]
	v_pk_mul_f32 v[64:65], v[64:65], s[76:77] op_sel_hi:[1,0]
	v_max_f32_e32 v66, 0, v50
	v_max_f32_e32 v67, 0, v51
	v_fma_f32 v50, -|v50|, v62, v66
	v_fma_f32 v51, -|v51|, v63, v67
	v_exp_f32_e32 v64, v64
	s_nop 0
	s_nop 0
	s_nop 0
	v_exp_f32_e32 v65, v65
	s_nop 0
	s_nop 0
	v_fma_f32 v62, |v52|, s64, 1.0
	v_fma_f32 v63, |v53|, s64, 1.0
	s_nop 0
	v_rcp_f32_e32 v62, v62
	v_rcp_f32_e32 v63, v63
	v_lshl_add_u64 v[58:59], v[160:161], 1, v[58:59]
	v_pk_mul_f32 v[42:43], v[42:43], v[0:1] op_sel_hi:[1,0]
	v_pk_mul_f32 v[44:45], v[44:45], v[0:1] op_sel_hi:[1,0]
	v_pk_fma_f32 v[66:67], v[62:63], s[66:67], v[46:47] op_sel_hi:[1,0,0]
	v_pk_mul_f32 v[40:41], v[40:41], v[0:1] op_sel_hi:[1,0]
	v_pk_fma_f32 v[66:67], v[62:63], v[66:67], s[70:71] op_sel_hi:[1,1,0]
	s_nop 0
	v_pk_fma_f32 v[66:67], v[62:63], v[66:67], s[72:73] op_sel_hi:[1,1,0]
	s_nop 0
	v_pk_fma_f32 v[66:67], v[62:63], v[66:67], s[74:75] op_sel_hi:[1,1,0]
	s_nop 0
	v_pk_mul_f32 v[62:63], v[62:63], v[66:67]
	v_pk_mul_f32 v[66:67], v[60:61], v[60:61]
	v_pk_mul_f32 v[62:63], v[64:65], v[62:63]
	v_pk_mul_f32 v[66:67], v[66:67], s[76:77] op_sel_hi:[1,0]
	v_max_f32_e32 v64, 0, v52
	v_max_f32_e32 v65, 0, v53
	v_fma_f32 v52, -|v52|, v62, v64
	v_fma_f32 v53, -|v53|, v63, v65
	v_exp_f32_e32 v66, v66
	s_nop 0
	s_nop 0
	s_nop 0
	v_exp_f32_e32 v67, v67
	s_nop 0
	s_nop 0
	v_fma_f32 v62, |v60|, s64, 1.0
	v_fma_f32 v63, |v61|, s64, 1.0
	s_nop 0
	v_rcp_f32_e32 v62, v62
	v_rcp_f32_e32 v63, v63
	s_nop 0
	v_pk_fma_f32 v[64:65], v[62:63], s[66:67], v[46:47] op_sel_hi:[1,0,0]
	s_nop 0
	v_pk_fma_f32 v[64:65], v[62:63], v[64:65], s[70:71] op_sel_hi:[1,1,0]
	s_nop 0
	v_pk_fma_f32 v[64:65], v[62:63], v[64:65], s[72:73] op_sel_hi:[1,1,0]
	s_nop 0
	v_pk_fma_f32 v[64:65], v[62:63], v[64:65], s[74:75] op_sel_hi:[1,1,0]
	s_nop 0
	v_pk_mul_f32 v[62:63], v[62:63], v[64:65]
	v_pk_mul_f32 v[64:65], v[48:49], v[48:49]
	v_pk_mul_f32 v[62:63], v[66:67], v[62:63]
	v_pk_mul_f32 v[64:65], v[64:65], s[76:77] op_sel_hi:[1,0]
	v_max_f32_e32 v66, 0, v60
	v_max_f32_e32 v67, 0, v61
	v_fma_f32 v60, -|v60|, v62, v66
	v_fma_f32 v61, -|v61|, v63, v67
	v_exp_f32_e32 v64, v64
	s_nop 0
	s_nop 0
	s_nop 0
	v_exp_f32_e32 v65, v65
	s_nop 0
	s_nop 0
	v_fma_f32 v62, |v48|, s64, 1.0
	v_fma_f32 v63, |v49|, s64, 1.0
	s_nop 0
	v_rcp_f32_e32 v62, v62
	v_rcp_f32_e32 v63, v63
	s_nop 0
	v_pk_fma_f32 v[66:67], v[62:63], s[66:67], v[46:47] op_sel_hi:[1,0,0]
	s_nop 0
	v_pk_fma_f32 v[66:67], v[62:63], v[66:67], s[70:71] op_sel_hi:[1,1,0]
	s_nop 0
	v_pk_fma_f32 v[66:67], v[62:63], v[66:67], s[72:73] op_sel_hi:[1,1,0]
	s_nop 0
	v_pk_fma_f32 v[66:67], v[62:63], v[66:67], s[74:75] op_sel_hi:[1,1,0]
	s_nop 0
	v_pk_mul_f32 v[62:63], v[62:63], v[66:67]
	v_pk_mul_f32 v[66:67], v[42:43], v[42:43]
	v_pk_mul_f32 v[62:63], v[64:65], v[62:63]
	v_pk_mul_f32 v[66:67], v[66:67], s[76:77] op_sel_hi:[1,0]
	v_max_f32_e32 v64, 0, v48
	v_max_f32_e32 v65, 0, v49
	v_fma_f32 v48, -|v48|, v62, v64
	v_fma_f32 v49, -|v49|, v63, v65
	v_exp_f32_e32 v66, v66
	s_nop 0
	s_nop 0
	v_cvt_pk_bf16_f32 v62, v50, v51
	v_exp_f32_e32 v67, v67
	s_nop 0
	s_nop 0
	v_cvt_pk_bf16_f32 v63, v52, v53
	v_cvt_pk_bf16_f32 v64, v60, v61
	v_cvt_pk_bf16_f32 v65, v48, v49
	global_store_dwordx4 v[58:59], v[62:65], off
	s_nop 0
	s_nop 0
	v_pk_mul_f32 v[62:63], v[38:39], v[0:1] op_sel_hi:[1,0]
	s_nop 0
	s_nop 0
	v_fma_f32 v38, |v42|, s64, 1.0
	v_fma_f32 v39, |v43|, s64, 1.0
	s_nop 0
	v_rcp_f32_e32 v38, v38
	v_rcp_f32_e32 v39, v39
	s_nop 0
	v_pk_fma_f32 v[64:65], v[38:39], s[66:67], v[46:47] op_sel_hi:[1,0,0]
	s_nop 0
	v_pk_fma_f32 v[64:65], v[38:39], v[64:65], s[70:71] op_sel_hi:[1,1,0]
	s_nop 0
	v_pk_fma_f32 v[64:65], v[38:39], v[64:65], s[72:73] op_sel_hi:[1,1,0]
	s_nop 0
	v_pk_fma_f32 v[64:65], v[38:39], v[64:65], s[74:75] op_sel_hi:[1,1,0]
	s_nop 0
	v_pk_mul_f32 v[38:39], v[38:39], v[64:65]
; __device__ __forceinline__ unsigned cvt_pk_bf16(float lo, float hi) { unsigned r; asm volatile("v_cvt_pk_bf16_f32 %0, %1, %2" : "=v"(r) : "v"(lo), "v"(hi)); return r; }
; __device__ __forceinline__ f32x2 gelu_pk(f32x2 v) {
;     const f32x2 av = __builtin_elementwise_abs(v), d = av * 0.2316418882f + 1.0f;
;     f32x2 t; t.x = __builtin_amdgcn_rcpf(d.x); t.y = __builtin_amdgcn_rcpf(d.y);
;     f32x2 q = t * 0.5307027145f + (-0.7265760135f); q = q * t + 0.7107068705f; q = q * t + (-0.142248368f); q = q * t + 0.127414796f; q = q * t;
;     const f32x2 s = (v * v) * (-0.72134752044f);
;     f32x2 e; e.x = __builtin_amdgcn_exp2f(s.x); e.y = __builtin_amdgcn_exp2f(s.y);
;     const f32x2 m = v * (q * e), r = v - m;
;     f32x2 o; o.x = v.x < 0.f ? m.x : r.x; o.y = v.y < 0.f ? m.y : r.y; return o;
;     __device__ __forceinline__ void operator()(const f32x4 (&acc)[2][2][4][2], const Unit& u, int wr, int wc, int fr, int fq) const {
;     ...
;                 for (int bj = 0; bj < 2; ++bj) { f32x4 v0 = acc[ai][bj][m][0] * rs, v1 = acc[ai][bj][m][1] * rs;
;                     const f32x2 a = gelu_pk((f32x2){v0[0], v0[1]}), b = gelu_pk((f32x2){v0[2], v0[3]}), c = gelu_pk((f32x2){v1[0], v1[1]}), d = gelu_pk((f32x2){v1[2], v1[3]});
;                     s1 += ((a.x + a.y) + (b.x + b.y)) + ((c.x + c.y) + (d.x + d.y));
;                     s2 += ((a.x * a.x + a.y * a.y) + (b.x * b.x + b.y * b.y)) + ((c.x * c.x + c.y * c.y) + (d.x * d.x + d.y * d.y));
;                     u32x4 w; w.x = cvt_pk_bf16(a.x, a.y); w.y = cvt_pk_bf16(b.x, b.y); w.z = cvt_pk_bf16(c.x, c.y); w.w = cvt_pk_bf16(d.x, d.y);
;                     *(u32x4*)(rowp + bj * HALF) = w; }
;                 if (isv) { s1 += __shfl_xor(s1, 16); s1 += __shfl_xor(s1, 32); s2 += __shfl_xor(s2, 16); s2 += __shfl_xor(s2, 32);
;                     if (fq == 0) { const int rl = ai * HALF + wr * 64 + m * 16 + fr; part[rl * 4 + wc] = s1; part[1024 + rl * 4 + wc] = s2; } } }
	v_pk_mul_f32 v[64:65], v[44:45], v[44:45]
	v_pk_mul_f32 v[38:39], v[66:67], v[38:39]
	v_pk_mul_f32 v[64:65], v[64:65], s[76:77] op_sel_hi:[1,0]
	v_max_f32_e32 v66, 0, v42
	v_max_f32_e32 v67, 0, v43
	v_fma_f32 v0, -|v42|, v38, v66
	v_fma_f32 v38, -|v43|, v39, v67
	s_nop 0
	s_nop 0
	s_nop 0
	s_nop 0
	v_fma_f32 v42, |v44|, s64, 1.0
	v_fma_f32 v43, |v45|, s64, 1.0
	s_nop 0
	v_rcp_f32_e32 v42, v42
	v_rcp_f32_e32 v43, v43
	v_exp_f32_e32 v64, v64
	v_exp_f32_e32 v65, v65
	s_nop 0
	v_pk_fma_f32 v[66:67], v[42:43], s[66:67], v[46:47] op_sel_hi:[1,0,0]
	s_nop 0
	v_pk_fma_f32 v[66:67], v[42:43], v[66:67], s[70:71] op_sel_hi:[1,1,0]
	s_nop 0
	v_pk_fma_f32 v[66:67], v[42:43], v[66:67], s[72:73] op_sel_hi:[1,1,0]
	s_nop 0
	v_pk_fma_f32 v[66:67], v[42:43], v[66:67], s[74:75] op_sel_hi:[1,1,0]
	s_nop 0
	v_pk_mul_f32 v[42:43], v[42:43], v[66:67]
	v_pk_mul_f32 v[66:67], v[62:63], v[62:63]
	v_pk_mul_f32 v[42:43], v[64:65], v[42:43]
	v_pk_mul_f32 v[66:67], v[66:67], s[76:77] op_sel_hi:[1,0]
	v_max_f32_e32 v64, 0, v44
	v_max_f32_e32 v65, 0, v45
	v_fma_f32 v39, -|v44|, v42, v64
	v_fma_f32 v42, -|v45|, v43, v65
	s_nop 0
	s_nop 0
	s_nop 0
	s_nop 0
	v_fma_f32 v44, |v62|, s64, 1.0
	v_fma_f32 v45, |v63|, s64, 1.0
	s_nop 0
	v_rcp_f32_e32 v44, v44
	v_rcp_f32_e32 v45, v45
	v_exp_f32_e32 v66, v66
	v_exp_f32_e32 v67, v67
	s_nop 0
	v_pk_fma_f32 v[64:65], v[44:45], s[66:67], v[46:47] op_sel_hi:[1,0,0]
	s_nop 0
	v_pk_fma_f32 v[64:65], v[44:45], v[64:65], s[70:71] op_sel_hi:[1,1,0]
	s_nop 0
	v_pk_fma_f32 v[64:65], v[44:45], v[64:65], s[72:73] op_sel_hi:[1,1,0]
	s_nop 0
	v_pk_fma_f32 v[64:65], v[44:45], v[64:65], s[74:75] op_sel_hi:[1,1,0]
	s_nop 0
	v_pk_mul_f32 v[44:45], v[44:45], v[64:65]
	v_pk_mul_f32 v[64:65], v[40:41], v[40:41]
	v_pk_mul_f32 v[44:45], v[66:67], v[44:45]
	s_nop 0
	v_max_f32_e32 v66, 0, v62
	v_max_f32_e32 v67, 0, v63
	v_fma_f32 v43, -|v62|, v44, v66
	v_fma_f32 v44, -|v63|, v45, v67
	s_nop 0
	s_nop 0
	s_nop 0
	s_nop 0
	v_fma_f32 v62, |v40|, s64, 1.0
	v_fma_f32 v63, |v41|, s64, 1.0
	s_nop 0
	v_rcp_f32_e32 v62, v62
	v_rcp_f32_e32 v63, v63
	s_nop 0
	v_pk_fma_f32 v[46:47], v[62:63], s[66:67], v[46:47] op_sel_hi:[1,0,0]
	s_nop 0
	v_pk_fma_f32 v[46:47], v[62:63], v[46:47], s[70:71] op_sel_hi:[1,1,0]
	s_nop 0
	v_pk_fma_f32 v[46:47], v[62:63], v[46:47], s[72:73] op_sel_hi:[1,1,0]
	s_nop 0
	v_pk_fma_f32 v[46:47], v[62:63], v[46:47], s[74:75] op_sel_hi:[1,1,0]
	s_nop 0
	v_pk_mul_f32 v[46:47], v[62:63], v[46:47]
	v_pk_mul_f32 v[62:63], v[64:65], s[76:77] op_sel_hi:[1,0]
	s_nop 0
	v_exp_f32_e32 v62, v62
	v_exp_f32_e32 v63, v63
	s_nop 0
	v_pk_mul_f32 v[46:47], v[62:63], v[46:47]
	s_nop 0
	v_max_f32_e32 v62, 0, v40
	v_max_f32_e32 v63, 0, v41
	v_fma_f32 v40, -|v40|, v46, v62
	v_fma_f32 v41, -|v41|, v47, v63
	s_nop 0
	s_nop 0
	s_nop 0
	v_cvt_pk_bf16_f32 v62, v0, v38
	s_nop 1
	s_nop 0
	s_and_b64 vcc, exec, s[10:11]
	v_cvt_pk_bf16_f32 v63, v39, v42
	v_cvt_pk_bf16_f32 v64, v43, v44
	v_cvt_pk_bf16_f32 v65, v40, v41
	global_store_dwordx4 v[58:59], v[62:65], off offset:256
	s_cbranch_vccnz .LBB0_376
	v_mul_f32_e32 v45, v51, v51
	v_mul_f32_e32 v46, v53, v53
	v_fmac_f32_e32 v45, v50, v50
	v_fmac_f32_e32 v46, v52, v52
	v_add_f32_e32 v45, v45, v46
	v_mul_f32_e32 v46, v61, v61
	v_mul_f32_e32 v47, v49, v49
	v_fmac_f32_e32 v46, v60, v60
	v_fmac_f32_e32 v47, v48, v48
	v_add_f32_e32 v46, v46, v47
	v_add_f32_e32 v45, v45, v46
	v_mul_f32_e32 v46, v38, v38
	v_fmac_f32_e32 v46, v0, v0
	v_mul_f32_e32 v47, v42, v42
	v_add_f32_e32 v0, v0, v38
	v_add_f32_e32 v38, v39, v42
	v_fmac_f32_e32 v47, v39, v39
	v_add_f32_e32 v50, v50, v51
	v_add_f32_e32 v51, v52, v53
	v_add_f32_e32 v0, v0, v38
	v_add_f32_e32 v38, v43, v44
	v_add_f32_e32 v39, v40, v41
	v_add_f32_e32 v50, v50, v51
	v_add_f32_e32 v51, v60, v61
	v_add_f32_e32 v48, v48, v49
	v_add_f32_e32 v38, v38, v39
	v_and_b32_e32 v39, 64, v226
	v_add_f32_e32 v48, v51, v48
	v_add_f32_e32 v0, v0, v38
	v_xor_b32_e32 v38, 16, v226
	v_add_u32_e32 v39, 64, v39
	v_add_f32_e32 v48, v50, v48
	v_cmp_lt_i32_e32 vcc, v38, v39
	v_add_f32_e32 v46, v46, v47
	v_mul_f32_e32 v47, v44, v44
	v_mul_f32_e32 v58, v41, v41
	v_add_f32_e32 v48, 0, v48
	v_cndmask_b32_e32 v38, v226, v38, vcc
	v_fmac_f32_e32 v47, v43, v43
	v_add_f32_e32 v0, v0, v48
	v_lshlrev_b32_e32 v38, 2, v38
	v_fmac_f32_e32 v58, v40, v40
	v_mov_b32_e32 v41, v0
	s_nop 1
	v_permlane16_swap_b32_e32 v41, v0
	v_add_f32_e32 v40, v47, v58
	v_add_f32_e32 v40, v46, v40
	v_add_f32_e32 v40, v45, v40
	v_mov_b32_e32 v42, v40
	s_nop 1
	v_permlane16_swap_b32_e32 v42, v40
	s_waitcnt lgkmcnt(0)
	v_add_f32_e32 v0, v0, v41
	v_xor_b32_e32 v41, 32, v226
	v_cmp_lt_i32_e32 vcc, v41, v39
	v_add_f32_e32 v39, v40, v42
	s_nop 0
	v_cndmask_b32_e32 v38, v226, v41, vcc
	v_lshlrev_b32_e32 v41, 2, v38
	v_mov_b32_e32 v38, v0
	s_nop 1
	v_permlane32_swap_b32_e32 v38, v0
	v_mov_b32_e32 v40, v39
	s_nop 1
	v_permlane32_swap_b32_e32 v40, v39
	s_and_saveexec_b64 s[4:5], s[6:7]
	s_cbranch_execz .LBB0_375
	s_waitcnt lgkmcnt(0)
	v_add_f32_e32 v39, v39, v40
	v_add_f32_e32 v0, v0, v38
	ds_write2st64_b32 v186, v0, v39 offset0:9 offset1:25

; __device__ __forceinline__ unsigned cvt_pk_bf16(float lo, float hi) { unsigned r; asm volatile("v_cvt_pk_bf16_f32 %0, %1, %2" : "=v"(r) : "v"(lo), "v"(hi)); return r; }
; __device__ __forceinline__ f32x2 gelu_pk(f32x2 v) {
;     const f32x2 av = __builtin_elementwise_abs(v), d = av * 0.2316418882f + 1.0f;
;     f32x2 t; t.x = __builtin_amdgcn_rcpf(d.x); t.y = __builtin_amdgcn_rcpf(d.y);
;     f32x2 q = t * 0.5307027145f + (-0.7265760135f); q = q * t + 0.7107068705f; q = q * t + (-0.142248368f); q = q * t + 0.127414796f; q = q * t;
;     const f32x2 s = (v * v) * (-0.72134752044f);
;     f32x2 e; e.x = __builtin_amdgcn_exp2f(s.x); e.y = __builtin_amdgcn_exp2f(s.y);
;     const f32x2 m = v * (q * e), r = v - m;
;     f32x2 o; o.x = v.x < 0.f ? m.x : r.x; o.y = v.y < 0.f ? m.y : r.y; return o;
;     __device__ __forceinline__ void operator()(const f32x4 (&acc)[2][2][4][2], const Unit& u, int wr, int wc, int fr, int fq) const {
;     ...
;             for (int m = 0; m < 4; ++m) { const int row = row0 + ai * HALF + m * 16; const float rs = rsv[ai][m]; bf16_t* rowp = O + (size_t)row * ldc + col0; float s1 = 0.f, s2 = 0.f;
; #pragma unroll
;                 for (int bj = 0; bj < 2; ++bj) { f32x4 v0 = acc[ai][bj][m][0] * rs, v1 = acc[ai][bj][m][1] * rs;
;                     const f32x2 a = gelu_pk((f32x2){v0[0], v0[1]}), b = gelu_pk((f32x2){v0[2], v0[3]}), c = gelu_pk((f32x2){v1[0], v1[1]}), d = gelu_pk((f32x2){v1[2], v1[3]});
;                     s1 += ((a.x + a.y) + (b.x + b.y)) + ((c.x + c.y) + (d.x + d.y));
;                     s2 += ((a.x * a.x + a.y * a.y) + (b.x * b.x + b.y * b.y)) + ((c.x * c.x + c.y * c.y) + (d.x * d.x + d.y * d.y));
;                     u32x4 w; w.x = cvt_pk_bf16(a.x, a.y); w.y = cvt_pk_bf16(b.x, b.y); w.z = cvt_pk_bf16(c.x, c.y); w.w = cvt_pk_bf16(d.x, d.y);
;                     *(u32x4*)(rowp + bj * HALF) = w; }
.LBB0_376:
	v_add_f32_e32 v0, v54, v55
	s_waitcnt lgkmcnt(0)
	v_add_f32_e32 v38, v56, v57
	v_add_f32_e32 v0, v0, v38
	v_fmamk_f32 v0, v0, 0x3a800000, v224
	v_rsq_f32_e32 v0, v0
	s_mov_b32 s4, 0xbf3a00e3
	v_lshlrev_b64 v[38:39], 12, v[164:165]
	v_lshl_add_u64 v[38:39], s[20:21], 0, v[38:39]
	v_pk_mul_f32 v[30:31], v[30:31], v[0:1] op_sel_hi:[1,0]
	v_pk_mul_f32 v[40:41], v[26:27], v[0:1] op_sel_hi:[1,0]
	s_nop 0
	s_nop 0
	v_fma_f32 v26, |v30|, s64, 1.0
	v_fma_f32 v27, |v31|, s64, 1.0
	v_pk_mul_f32 v[46:47], v[30:31], v[30:31]
	v_rcp_f32_e32 v42, v26
	v_rcp_f32_e32 v43, v27
	v_mov_b64_e32 v[26:27], s[4:5]
	v_pk_mul_f32 v[46:47], v[46:47], s[76:77] op_sel_hi:[1,0]
	s_nop 0
	v_pk_fma_f32 v[44:45], v[42:43], s[66:67], v[26:27] op_sel_hi:[1,0,0]
	v_exp_f32_e32 v46, v46
	v_pk_fma_f32 v[44:45], v[42:43], v[44:45], s[70:71] op_sel_hi:[1,1,0]
	v_exp_f32_e32 v47, v47
	v_pk_fma_f32 v[44:45], v[42:43], v[44:45], s[72:73] op_sel_hi:[1,1,0]
	v_pk_mul_f32 v[32:33], v[32:33], v[0:1] op_sel_hi:[1,0]
	v_pk_fma_f32 v[44:45], v[42:43], v[44:45], s[74:75] op_sel_hi:[1,1,0]
	v_pk_mul_f32 v[28:29], v[28:29], v[0:1] op_sel_hi:[1,0]
	v_pk_mul_f32 v[42:43], v[42:43], v[44:45]
	v_pk_mul_f32 v[44:45], v[32:33], v[32:33]
	v_pk_mul_f32 v[42:43], v[46:47], v[42:43]
	v_pk_mul_f32 v[44:45], v[44:45], s[76:77] op_sel_hi:[1,0]
	v_max_f32_e32 v46, 0, v30
	v_max_f32_e32 v47, 0, v31
	v_fma_f32 v30, -|v30|, v42, v46
	v_fma_f32 v31, -|v31|, v43, v47
	v_exp_f32_e32 v44, v44
	s_nop 0
	s_nop 0
	s_nop 0
	v_exp_f32_e32 v45, v45
	s_nop 0
	s_nop 0
	v_fma_f32 v42, |v32|, s64, 1.0
	v_fma_f32 v43, |v33|, s64, 1.0
	s_nop 0
	v_rcp_f32_e32 v42, v42
	v_rcp_f32_e32 v43, v43
	v_lshl_add_u64 v[38:39], v[160:161], 1, v[38:39]
	v_pk_mul_f32 v[22:23], v[22:23], v[0:1] op_sel_hi:[1,0]
	v_pk_mul_f32 v[24:25], v[24:25], v[0:1] op_sel_hi:[1,0]
	v_pk_fma_f32 v[46:47], v[42:43], s[66:67], v[26:27] op_sel_hi:[1,0,0]
	v_pk_mul_f32 v[20:21], v[20:21], v[0:1] op_sel_hi:[1,0]
	v_pk_fma_f32 v[46:47], v[42:43], v[46:47], s[70:71] op_sel_hi:[1,1,0]
	s_nop 0
	v_pk_fma_f32 v[46:47], v[42:43], v[46:47], s[72:73] op_sel_hi:[1,1,0]
	s_nop 0
	v_pk_fma_f32 v[46:47], v[42:43], v[46:47], s[74:75] op_sel_hi:[1,1,0]
	s_nop 0
	v_pk_mul_f32 v[42:43], v[42:43], v[46:47]
	v_pk_mul_f32 v[46:47], v[40:41], v[40:41]
	v_pk_mul_f32 v[42:43], v[44:45], v[42:43]
	v_pk_mul_f32 v[46:47], v[46:47], s[76:77] op_sel_hi:[1,0]
	v_max_f32_e32 v44, 0, v32
	v_max_f32_e32 v45, 0, v33
	v_fma_f32 v32, -|v32|, v42, v44
	v_fma_f32 v33, -|v33|, v43, v45
	v_exp_f32_e32 v46, v46
	s_nop 0
	s_nop 0
	s_nop 0
	v_exp_f32_e32 v47, v47
	s_nop 0
	s_nop 0
	v_fma_f32 v42, |v40|, s64, 1.0
	v_fma_f32 v43, |v41|, s64, 1.0
	s_nop 0
	v_rcp_f32_e32 v42, v42
	v_rcp_f32_e32 v43, v43
	s_nop 0
	v_pk_fma_f32 v[44:45], v[42:43], s[66:67], v[26:27] op_sel_hi:[1,0,0]
	s_nop 0
	v_pk_fma_f32 v[44:45], v[42:43], v[44:45], s[70:71] op_sel_hi:[1,1,0]
	s_nop 0
	v_pk_fma_f32 v[44:45], v[42:43], v[44:45], s[72:73] op_sel_hi:[1,1,0]
	s_nop 0
	v_pk_fma_f32 v[44:45], v[42:43], v[44:45], s[74:75] op_sel_hi:[1,1,0]
	s_nop 0
	v_pk_mul_f32 v[42:43], v[42:43], v[44:45]
	v_pk_mul_f32 v[44:45], v[28:29], v[28:29]
	v_pk_mul_f32 v[42:43], v[46:47], v[42:43]
	v_pk_mul_f32 v[44:45], v[44:45], s[76:77] op_sel_hi:[1,0]
	v_max_f32_e32 v46, 0, v40
	v_max_f32_e32 v47, 0, v41
	v_fma_f32 v40, -|v40|, v42, v46
	v_fma_f32 v41, -|v41|, v43, v47
	v_exp_f32_e32 v44, v44
	s_nop 0
	s_nop 0
	s_nop 0
	v_exp_f32_e32 v45, v45
	s_nop 0
	s_nop 0
	v_fma_f32 v42, |v28|, s64, 1.0
	v_fma_f32 v43, |v29|, s64, 1.0
	s_nop 0
	v_rcp_f32_e32 v42, v42
	v_rcp_f32_e32 v43, v43
	s_nop 0
	v_pk_fma_f32 v[46:47], v[42:43], s[66:67], v[26:27] op_sel_hi:[1,0,0]
	s_nop 0
	v_pk_fma_f32 v[46:47], v[42:43], v[46:47], s[70:71] op_sel_hi:[1,1,0]
	s_nop 0
	v_pk_fma_f32 v[46:47], v[42:43], v[46:47], s[72:73] op_sel_hi:[1,1,0]
	s_nop 0
	v_pk_fma_f32 v[46:47], v[42:43], v[46:47], s[74:75] op_sel_hi:[1,1,0]
	s_nop 0
	v_pk_mul_f32 v[42:43], v[42:43], v[46:47]
	v_pk_mul_f32 v[46:47], v[22:23], v[22:23]
	v_pk_mul_f32 v[42:43], v[44:45], v[42:43]
	v_pk_mul_f32 v[46:47], v[46:47], s[76:77] op_sel_hi:[1,0]
	v_max_f32_e32 v44, 0, v28
	v_max_f32_e32 v45, 0, v29
	v_fma_f32 v28, -|v28|, v42, v44
	v_fma_f32 v29, -|v29|, v43, v45
	v_exp_f32_e32 v46, v46
	s_nop 0
	s_nop 0
	v_cvt_pk_bf16_f32 v42, v30, v31
	v_exp_f32_e32 v47, v47
	s_nop 0
	s_nop 0
	v_cvt_pk_bf16_f32 v43, v32, v33
	v_cvt_pk_bf16_f32 v44, v40, v41
	v_cvt_pk_bf16_f32 v45, v28, v29
	global_store_dwordx4 v[38:39], v[42:45], off
	s_nop 0
	s_nop 0
	v_pk_mul_f32 v[42:43], v[18:19], v[0:1] op_sel_hi:[1,0]
	s_nop 0
	s_nop 0
	v_fma_f32 v18, |v22|, s64, 1.0
	v_fma_f32 v19, |v23|, s64, 1.0
	s_nop 0
	v_rcp_f32_e32 v18, v18
	v_rcp_f32_e32 v19, v19
	s_nop 0
	v_pk_fma_f32 v[44:45], v[18:19], s[66:67], v[26:27] op_sel_hi:[1,0,0]
	s_nop 0
	v_pk_fma_f32 v[44:45], v[18:19], v[44:45], s[70:71] op_sel_hi:[1,1,0]
	s_nop 0
	v_pk_fma_f32 v[44:45], v[18:19], v[44:45], s[72:73] op_sel_hi:[1,1,0]
	s_nop 0
	v_pk_fma_f32 v[44:45], v[18:19], v[44:45], s[74:75] op_sel_hi:[1,1,0]
	s_nop 0
	v_pk_mul_f32 v[18:19], v[18:19], v[44:45]
; __device__ __forceinline__ unsigned cvt_pk_bf16(float lo, float hi) { unsigned r; asm volatile("v_cvt_pk_bf16_f32 %0, %1, %2" : "=v"(r) : "v"(lo), "v"(hi)); return r; }
; __device__ __forceinline__ f32x2 gelu_pk(f32x2 v) {
;     const f32x2 av = __builtin_elementwise_abs(v), d = av * 0.2316418882f + 1.0f;
;     f32x2 t; t.x = __builtin_amdgcn_rcpf(d.x); t.y = __builtin_amdgcn_rcpf(d.y);
;     f32x2 q = t * 0.5307027145f + (-0.7265760135f); q = q * t + 0.7107068705f; q = q * t + (-0.142248368f); q = q * t + 0.127414796f; q = q * t;
;     const f32x2 s = (v * v) * (-0.72134752044f);
;     f32x2 e; e.x = __builtin_amdgcn_exp2f(s.x); e.y = __builtin_amdgcn_exp2f(s.y);
;     const f32x2 m = v * (q * e), r = v - m;
;     f32x2 o; o.x = v.x < 0.f ? m.x : r.x; o.y = v.y < 0.f ? m.y : r.y; return o;
;     __device__ __forceinline__ void operator()(const f32x4 (&acc)[2][2][4][2], const Unit& u, int wr, int wc, int fr, int fq) const {
;     ...
;                 for (int bj = 0; bj < 2; ++bj) { f32x4 v0 = acc[ai][bj][m][0] * rs, v1 = acc[ai][bj][m][1] * rs;
;                     const f32x2 a = gelu_pk((f32x2){v0[0], v0[1]}), b = gelu_pk((f32x2){v0[2], v0[3]}), c = gelu_pk((f32x2){v1[0], v1[1]}), d = gelu_pk((f32x2){v1[2], v1[3]});
;                     s1 += ((a.x + a.y) + (b.x + b.y)) + ((c.x + c.y) + (d.x + d.y));
;                     s2 += ((a.x * a.x + a.y * a.y) + (b.x * b.x + b.y * b.y)) + ((c.x * c.x + c.y * c.y) + (d.x * d.x + d.y * d.y));
;                     u32x4 w; w.x = cvt_pk_bf16(a.x, a.y); w.y = cvt_pk_bf16(b.x, b.y); w.z = cvt_pk_bf16(c.x, c.y); w.w = cvt_pk_bf16(d.x, d.y);
;                     *(u32x4*)(rowp + bj * HALF) = w; }
;                 if (isv) { s1 += __shfl_xor(s1, 16); s1 += __shfl_xor(s1, 32); s2 += __shfl_xor(s2, 16); s2 += __shfl_xor(s2, 32);
;                     if (fq == 0) { const int rl = ai * HALF + wr * 64 + m * 16 + fr; part[rl * 4 + wc] = s1; part[1024 + rl * 4 + wc] = s2; } } }
	v_pk_mul_f32 v[44:45], v[24:25], v[24:25]
	v_pk_mul_f32 v[18:19], v[46:47], v[18:19]
	v_pk_mul_f32 v[44:45], v[44:45], s[76:77] op_sel_hi:[1,0]
	v_max_f32_e32 v46, 0, v22
	v_max_f32_e32 v47, 0, v23
	v_fma_f32 v0, -|v22|, v18, v46
	v_fma_f32 v18, -|v23|, v19, v47
	s_nop 0
	s_nop 0
	s_nop 0
	s_nop 0
	v_fma_f32 v22, |v24|, s64, 1.0
	v_fma_f32 v23, |v25|, s64, 1.0
	s_nop 0
	v_rcp_f32_e32 v22, v22
	v_rcp_f32_e32 v23, v23
	v_exp_f32_e32 v44, v44
	v_exp_f32_e32 v45, v45
	s_nop 0
	v_pk_fma_f32 v[46:47], v[22:23], s[66:67], v[26:27] op_sel_hi:[1,0,0]
	s_nop 0
	v_pk_fma_f32 v[46:47], v[22:23], v[46:47], s[70:71] op_sel_hi:[1,1,0]
	s_nop 0
	v_pk_fma_f32 v[46:47], v[22:23], v[46:47], s[72:73] op_sel_hi:[1,1,0]
	s_nop 0
	v_pk_fma_f32 v[46:47], v[22:23], v[46:47], s[74:75] op_sel_hi:[1,1,0]
	s_nop 0
	v_pk_mul_f32 v[22:23], v[22:23], v[46:47]
	v_pk_mul_f32 v[46:47], v[42:43], v[42:43]
	v_pk_mul_f32 v[22:23], v[44:45], v[22:23]
	v_pk_mul_f32 v[46:47], v[46:47], s[76:77] op_sel_hi:[1,0]
	v_max_f32_e32 v44, 0, v24
	v_max_f32_e32 v45, 0, v25
	v_fma_f32 v19, -|v24|, v22, v44
	v_fma_f32 v22, -|v25|, v23, v45
	s_nop 0
	s_nop 0
	s_nop 0
	s_nop 0
	v_fma_f32 v24, |v42|, s64, 1.0
	v_fma_f32 v25, |v43|, s64, 1.0
	s_nop 0
	v_rcp_f32_e32 v24, v24
	v_rcp_f32_e32 v25, v25
	v_exp_f32_e32 v46, v46
	v_exp_f32_e32 v47, v47
	s_nop 0
	v_pk_fma_f32 v[44:45], v[24:25], s[66:67], v[26:27] op_sel_hi:[1,0,0]
	s_nop 0
	v_pk_fma_f32 v[44:45], v[24:25], v[44:45], s[70:71] op_sel_hi:[1,1,0]
	s_nop 0
	v_pk_fma_f32 v[44:45], v[24:25], v[44:45], s[72:73] op_sel_hi:[1,1,0]
	s_nop 0
	v_pk_fma_f32 v[44:45], v[24:25], v[44:45], s[74:75] op_sel_hi:[1,1,0]
	s_nop 0
	v_pk_mul_f32 v[24:25], v[24:25], v[44:45]
	v_pk_mul_f32 v[44:45], v[20:21], v[20:21]
	v_pk_mul_f32 v[24:25], v[46:47], v[24:25]
	s_nop 0
	v_max_f32_e32 v46, 0, v42
	v_max_f32_e32 v47, 0, v43
	v_fma_f32 v23, -|v42|, v24, v46
	v_fma_f32 v24, -|v43|, v25, v47
	s_nop 0
	s_nop 0
	s_nop 0
	s_nop 0
	v_fma_f32 v42, |v20|, s64, 1.0
	v_fma_f32 v43, |v21|, s64, 1.0
	s_nop 0
	v_rcp_f32_e32 v42, v42
	v_rcp_f32_e32 v43, v43
	s_nop 0
	v_pk_fma_f32 v[26:27], v[42:43], s[66:67], v[26:27] op_sel_hi:[1,0,0]
	s_nop 0
	v_pk_fma_f32 v[26:27], v[42:43], v[26:27], s[70:71] op_sel_hi:[1,1,0]
	s_nop 0
	v_pk_fma_f32 v[26:27], v[42:43], v[26:27], s[72:73] op_sel_hi:[1,1,0]
	s_nop 0
	v_pk_fma_f32 v[26:27], v[42:43], v[26:27], s[74:75] op_sel_hi:[1,1,0]
	s_nop 0
	v_pk_mul_f32 v[26:27], v[42:43], v[26:27]
	v_pk_mul_f32 v[42:43], v[44:45], s[76:77] op_sel_hi:[1,0]
	s_nop 0
	v_exp_f32_e32 v42, v42
	v_exp_f32_e32 v43, v43
	s_nop 0
	v_pk_mul_f32 v[26:27], v[42:43], v[26:27]
	s_nop 0
	v_max_f32_e32 v42, 0, v20
	v_max_f32_e32 v43, 0, v21
	v_fma_f32 v20, -|v20|, v26, v42
	v_fma_f32 v21, -|v21|, v27, v43
	s_nop 0
	s_nop 0
	s_nop 0
	v_cvt_pk_bf16_f32 v42, v0, v18
	s_nop 1
	s_nop 0
	s_and_b64 vcc, exec, s[10:11]
	v_cvt_pk_bf16_f32 v43, v19, v22
	v_cvt_pk_bf16_f32 v44, v23, v24
	v_cvt_pk_bf16_f32 v45, v20, v21
	global_store_dwordx4 v[38:39], v[42:45], off offset:256
	s_cbranch_vccnz .LBB0_380
	v_mul_f32_e32 v25, v31, v31
	v_mul_f32_e32 v26, v33, v33
	v_fmac_f32_e32 v25, v30, v30
	v_fmac_f32_e32 v26, v32, v32
	v_add_f32_e32 v25, v25, v26
	v_mul_f32_e32 v26, v41, v41
	v_mul_f32_e32 v27, v29, v29
	v_fmac_f32_e32 v26, v40, v40
	v_fmac_f32_e32 v27, v28, v28
	v_add_f32_e32 v26, v26, v27
	v_add_f32_e32 v25, v25, v26
	v_mul_f32_e32 v26, v18, v18
	v_fmac_f32_e32 v26, v0, v0
	v_mul_f32_e32 v27, v22, v22
	v_add_f32_e32 v0, v0, v18
	v_add_f32_e32 v18, v19, v22
	v_fmac_f32_e32 v27, v19, v19
	v_add_f32_e32 v30, v30, v31
	v_add_f32_e32 v31, v32, v33
	v_add_f32_e32 v0, v0, v18
	v_add_f32_e32 v18, v23, v24
	v_add_f32_e32 v19, v20, v21
	v_add_f32_e32 v30, v30, v31
	v_add_f32_e32 v31, v40, v41
	v_add_f32_e32 v28, v28, v29
	v_add_f32_e32 v18, v18, v19
	v_and_b32_e32 v19, 64, v226
	v_add_f32_e32 v28, v31, v28
	v_add_f32_e32 v0, v0, v18
	v_xor_b32_e32 v18, 16, v226
	v_add_u32_e32 v19, 64, v19
	v_add_f32_e32 v28, v30, v28
	v_cmp_lt_i32_e32 vcc, v18, v19
	v_add_f32_e32 v26, v26, v27
	v_mul_f32_e32 v27, v24, v24
	v_mul_f32_e32 v38, v21, v21
	v_add_f32_e32 v28, 0, v28
	v_cndmask_b32_e32 v18, v226, v18, vcc
	v_fmac_f32_e32 v27, v23, v23
	v_add_f32_e32 v0, v0, v28
	v_lshlrev_b32_e32 v18, 2, v18
	v_fmac_f32_e32 v38, v20, v20
	v_mov_b32_e32 v21, v0
	s_nop 1
	v_permlane16_swap_b32_e32 v21, v0
	v_add_f32_e32 v20, v27, v38
	v_add_f32_e32 v20, v26, v20
	v_add_f32_e32 v20, v25, v20
	v_mov_b32_e32 v22, v20
	s_nop 1
	v_permlane16_swap_b32_e32 v22, v20
	s_waitcnt lgkmcnt(0)
	v_add_f32_e32 v0, v0, v21
	v_xor_b32_e32 v21, 32, v226
	v_cmp_lt_i32_e32 vcc, v21, v19
	v_add_f32_e32 v19, v20, v22
	s_nop 0
	v_cndmask_b32_e32 v18, v226, v21, vcc
	v_lshlrev_b32_e32 v21, 2, v18
	v_mov_b32_e32 v18, v0
	s_nop 1
	v_permlane32_swap_b32_e32 v18, v0
	v_mov_b32_e32 v20, v19
	s_nop 1
	v_permlane32_swap_b32_e32 v20, v19
	s_and_saveexec_b64 s[4:5], s[6:7]
	s_cbranch_execz .LBB0_379
	s_waitcnt lgkmcnt(0)
	v_add_f32_e32 v19, v19, v20
	v_add_f32_e32 v0, v0, v18
	ds_write2st64_b32 v186, v0, v19 offset0:10 offset1:26

; __device__ __forceinline__ unsigned cvt_pk_bf16(float lo, float hi) { unsigned r; asm volatile("v_cvt_pk_bf16_f32 %0, %1, %2" : "=v"(r) : "v"(lo), "v"(hi)); return r; }
; __device__ __forceinline__ f32x2 gelu_pk(f32x2 v) {
;     const f32x2 av = __builtin_elementwise_abs(v), d = av * 0.2316418882f + 1.0f;
;     f32x2 t; t.x = __builtin_amdgcn_rcpf(d.x); t.y = __builtin_amdgcn_rcpf(d.y);
;     f32x2 q = t * 0.5307027145f + (-0.7265760135f); q = q * t + 0.7107068705f; q = q * t + (-0.142248368f); q = q * t + 0.127414796f; q = q * t;
;     const f32x2 s = (v * v) * (-0.72134752044f);
;     f32x2 e; e.x = __builtin_amdgcn_exp2f(s.x); e.y = __builtin_amdgcn_exp2f(s.y);
;     const f32x2 m = v * (q * e), r = v - m;
;     f32x2 o; o.x = v.x < 0.f ? m.x : r.x; o.y = v.y < 0.f ? m.y : r.y; return o;
;     __device__ __forceinline__ void operator()(const f32x4 (&acc)[2][2][4][2], const Unit& u, int wr, int wc, int fr, int fq) const {
;     ...
;             for (int m = 0; m < 4; ++m) { const int row = row0 + ai * HALF + m * 16; const float rs = rsv[ai][m]; bf16_t* rowp = O + (size_t)row * ldc + col0; float s1 = 0.f, s2 = 0.f;
; #pragma unroll
;                 for (int bj = 0; bj < 2; ++bj) { f32x4 v0 = acc[ai][bj][m][0] * rs, v1 = acc[ai][bj][m][1] * rs;
;                     const f32x2 a = gelu_pk((f32x2){v0[0], v0[1]}), b = gelu_pk((f32x2){v0[2], v0[3]}), c = gelu_pk((f32x2){v1[0], v1[1]}), d = gelu_pk((f32x2){v1[2], v1[3]});
;                     s1 += ((a.x + a.y) + (b.x + b.y)) + ((c.x + c.y) + (d.x + d.y));
;                     s2 += ((a.x * a.x + a.y * a.y) + (b.x * b.x + b.y * b.y)) + ((c.x * c.x + c.y * c.y) + (d.x * d.x + d.y * d.y));
;                     u32x4 w; w.x = cvt_pk_bf16(a.x, a.y); w.y = cvt_pk_bf16(b.x, b.y); w.z = cvt_pk_bf16(c.x, c.y); w.w = cvt_pk_bf16(d.x, d.y);
;                     *(u32x4*)(rowp + bj * HALF) = w; }
.LBB0_380:
	v_add_f32_e32 v0, v34, v35
	s_waitcnt lgkmcnt(0)
	v_add_f32_e32 v18, v36, v37
	v_add_f32_e32 v0, v0, v18
	v_fmamk_f32 v0, v0, 0x3a800000, v224
	v_rsq_f32_e32 v0, v0
	s_mov_b32 s4, 0xbf3a00e3
	v_lshlrev_b64 v[18:19], 12, v[162:163]
	v_lshl_add_u64 v[18:19], s[20:21], 0, v[18:19]
	v_pk_mul_f32 v[14:15], v[14:15], v[0:1] op_sel_hi:[1,0]
	v_pk_mul_f32 v[20:21], v[10:11], v[0:1] op_sel_hi:[1,0]
	s_nop 0
	s_nop 0
	v_fma_f32 v10, |v14|, s64, 1.0
	v_fma_f32 v11, |v15|, s64, 1.0
	v_pk_mul_f32 v[26:27], v[14:15], v[14:15]
	v_rcp_f32_e32 v22, v10
	v_rcp_f32_e32 v23, v11
	v_mov_b64_e32 v[10:11], s[4:5]
	v_pk_mul_f32 v[26:27], v[26:27], s[76:77] op_sel_hi:[1,0]
	s_nop 0
	v_pk_fma_f32 v[24:25], v[22:23], s[66:67], v[10:11] op_sel_hi:[1,0,0]
	v_exp_f32_e32 v26, v26
	v_pk_fma_f32 v[24:25], v[22:23], v[24:25], s[70:71] op_sel_hi:[1,1,0]
	v_exp_f32_e32 v27, v27
	v_pk_fma_f32 v[24:25], v[22:23], v[24:25], s[72:73] op_sel_hi:[1,1,0]
	v_pk_mul_f32 v[16:17], v[16:17], v[0:1] op_sel_hi:[1,0]
	v_pk_fma_f32 v[24:25], v[22:23], v[24:25], s[74:75] op_sel_hi:[1,1,0]
	v_pk_mul_f32 v[12:13], v[12:13], v[0:1] op_sel_hi:[1,0]
	v_pk_mul_f32 v[22:23], v[22:23], v[24:25]
	v_pk_mul_f32 v[24:25], v[16:17], v[16:17]
	v_pk_mul_f32 v[22:23], v[26:27], v[22:23]
	v_pk_mul_f32 v[24:25], v[24:25], s[76:77] op_sel_hi:[1,0]
	v_max_f32_e32 v26, 0, v14
	v_max_f32_e32 v27, 0, v15
	v_fma_f32 v14, -|v14|, v22, v26
	v_fma_f32 v15, -|v15|, v23, v27
	v_exp_f32_e32 v24, v24
	s_nop 0
	s_nop 0
	s_nop 0
	v_exp_f32_e32 v25, v25
	s_nop 0
	s_nop 0
	v_fma_f32 v22, |v16|, s64, 1.0
	v_fma_f32 v23, |v17|, s64, 1.0
	s_nop 0
	v_rcp_f32_e32 v22, v22
	v_rcp_f32_e32 v23, v23
	v_lshl_add_u64 v[18:19], v[160:161], 1, v[18:19]
	v_pk_mul_f32 v[6:7], v[6:7], v[0:1] op_sel_hi:[1,0]
	v_pk_mul_f32 v[8:9], v[8:9], v[0:1] op_sel_hi:[1,0]
	v_pk_fma_f32 v[26:27], v[22:23], s[66:67], v[10:11] op_sel_hi:[1,0,0]
	v_pk_mul_f32 v[4:5], v[4:5], v[0:1] op_sel_hi:[1,0]
	v_pk_fma_f32 v[26:27], v[22:23], v[26:27], s[70:71] op_sel_hi:[1,1,0]
	s_nop 0
	v_pk_fma_f32 v[26:27], v[22:23], v[26:27], s[72:73] op_sel_hi:[1,1,0]
	s_nop 0
	v_pk_fma_f32 v[26:27], v[22:23], v[26:27], s[74:75] op_sel_hi:[1,1,0]
	s_nop 0
	v_pk_mul_f32 v[22:23], v[22:23], v[26:27]
	v_pk_mul_f32 v[26:27], v[20:21], v[20:21]
	v_pk_mul_f32 v[22:23], v[24:25], v[22:23]
	v_pk_mul_f32 v[26:27], v[26:27], s[76:77] op_sel_hi:[1,0]
	v_max_f32_e32 v24, 0, v16
	v_max_f32_e32 v25, 0, v17
	v_fma_f32 v16, -|v16|, v22, v24
	v_fma_f32 v17, -|v17|, v23, v25
	v_exp_f32_e32 v26, v26
	s_nop 0
	s_nop 0
	s_nop 0
	v_exp_f32_e32 v27, v27
	s_nop 0
	s_nop 0
	v_fma_f32 v22, |v20|, s64, 1.0
	v_fma_f32 v23, |v21|, s64, 1.0
	s_nop 0
	v_rcp_f32_e32 v22, v22
	v_rcp_f32_e32 v23, v23
	s_nop 0
	v_pk_fma_f32 v[24:25], v[22:23], s[66:67], v[10:11] op_sel_hi:[1,0,0]
	s_nop 0
	v_pk_fma_f32 v[24:25], v[22:23], v[24:25], s[70:71] op_sel_hi:[1,1,0]
	s_nop 0
	v_pk_fma_f32 v[24:25], v[22:23], v[24:25], s[72:73] op_sel_hi:[1,1,0]
	s_nop 0
	v_pk_fma_f32 v[24:25], v[22:23], v[24:25], s[74:75] op_sel_hi:[1,1,0]
	s_nop 0
	v_pk_mul_f32 v[22:23], v[22:23], v[24:25]
	v_pk_mul_f32 v[24:25], v[12:13], v[12:13]
	v_pk_mul_f32 v[22:23], v[26:27], v[22:23]
	v_pk_mul_f32 v[24:25], v[24:25], s[76:77] op_sel_hi:[1,0]
	v_max_f32_e32 v26, 0, v20
	v_max_f32_e32 v27, 0, v21
	v_fma_f32 v20, -|v20|, v22, v26
	v_fma_f32 v21, -|v21|, v23, v27
	v_exp_f32_e32 v24, v24
	s_nop 0
	s_nop 0
	s_nop 0
	v_exp_f32_e32 v25, v25
	s_nop 0
	s_nop 0
	v_fma_f32 v22, |v12|, s64, 1.0
	v_fma_f32 v23, |v13|, s64, 1.0
	s_nop 0
	v_rcp_f32_e32 v22, v22
	v_rcp_f32_e32 v23, v23
	s_nop 0
	v_pk_fma_f32 v[26:27], v[22:23], s[66:67], v[10:11] op_sel_hi:[1,0,0]
	s_nop 0
	v_pk_fma_f32 v[26:27], v[22:23], v[26:27], s[70:71] op_sel_hi:[1,1,0]
	s_nop 0
	v_pk_fma_f32 v[26:27], v[22:23], v[26:27], s[72:73] op_sel_hi:[1,1,0]
	s_nop 0
	v_pk_fma_f32 v[26:27], v[22:23], v[26:27], s[74:75] op_sel_hi:[1,1,0]
	s_nop 0
	v_pk_mul_f32 v[22:23], v[22:23], v[26:27]
	v_pk_mul_f32 v[26:27], v[6:7], v[6:7]
	v_pk_mul_f32 v[22:23], v[24:25], v[22:23]
	v_pk_mul_f32 v[26:27], v[26:27], s[76:77] op_sel_hi:[1,0]
	v_max_f32_e32 v24, 0, v12
	v_max_f32_e32 v25, 0, v13
	v_fma_f32 v12, -|v12|, v22, v24
	v_fma_f32 v13, -|v13|, v23, v25
	v_exp_f32_e32 v26, v26
	s_nop 0
	s_nop 0
	v_cvt_pk_bf16_f32 v22, v14, v15
	v_exp_f32_e32 v27, v27
	s_nop 0
	s_nop 0
	v_cvt_pk_bf16_f32 v23, v16, v17
	v_cvt_pk_bf16_f32 v24, v20, v21
	v_cvt_pk_bf16_f32 v25, v12, v13
	global_store_dwordx4 v[18:19], v[22:25], off
	s_nop 0
	s_nop 0
	v_pk_mul_f32 v[22:23], v[2:3], v[0:1] op_sel_hi:[1,0]
	s_nop 0
	s_nop 0
	v_fma_f32 v2, |v6|, s64, 1.0
	v_fma_f32 v3, |v7|, s64, 1.0
	s_nop 0
	v_rcp_f32_e32 v2, v2
	v_rcp_f32_e32 v3, v3
	s_nop 0
	v_pk_fma_f32 v[24:25], v[2:3], s[66:67], v[10:11] op_sel_hi:[1,0,0]
	s_nop 0
	v_pk_fma_f32 v[24:25], v[2:3], v[24:25], s[70:71] op_sel_hi:[1,1,0]
	s_nop 0
	v_pk_fma_f32 v[24:25], v[2:3], v[24:25], s[72:73] op_sel_hi:[1,1,0]
	s_nop 0
	v_pk_fma_f32 v[24:25], v[2:3], v[24:25], s[74:75] op_sel_hi:[1,1,0]
; __device__ __forceinline__ unsigned cvt_pk_bf16(float lo, float hi) { unsigned r; asm volatile("v_cvt_pk_bf16_f32 %0, %1, %2" : "=v"(r) : "v"(lo), "v"(hi)); return r; }
; __device__ __forceinline__ f32x2 gelu_pk(f32x2 v) {
;     const f32x2 av = __builtin_elementwise_abs(v), d = av * 0.2316418882f + 1.0f;
;     f32x2 t; t.x = __builtin_amdgcn_rcpf(d.x); t.y = __builtin_amdgcn_rcpf(d.y);
;     f32x2 q = t * 0.5307027145f + (-0.7265760135f); q = q * t + 0.7107068705f; q = q * t + (-0.142248368f); q = q * t + 0.127414796f; q = q * t;
;     const f32x2 s = (v * v) * (-0.72134752044f);
;     f32x2 e; e.x = __builtin_amdgcn_exp2f(s.x); e.y = __builtin_amdgcn_exp2f(s.y);
;     const f32x2 m = v * (q * e), r = v - m;
;     f32x2 o; o.x = v.x < 0.f ? m.x : r.x; o.y = v.y < 0.f ? m.y : r.y; return o;
;     __device__ __forceinline__ void operator()(const f32x4 (&acc)[2][2][4][2], const Unit& u, int wr, int wc, int fr, int fq) const {
;     ...
;                 for (int bj = 0; bj < 2; ++bj) { f32x4 v0 = acc[ai][bj][m][0] * rs, v1 = acc[ai][bj][m][1] * rs;
;                     const f32x2 a = gelu_pk((f32x2){v0[0], v0[1]}), b = gelu_pk((f32x2){v0[2], v0[3]}), c = gelu_pk((f32x2){v1[0], v1[1]}), d = gelu_pk((f32x2){v1[2], v1[3]});
;                     s1 += ((a.x + a.y) + (b.x + b.y)) + ((c.x + c.y) + (d.x + d.y));
;                     s2 += ((a.x * a.x + a.y * a.y) + (b.x * b.x + b.y * b.y)) + ((c.x * c.x + c.y * c.y) + (d.x * d.x + d.y * d.y));
;                     u32x4 w; w.x = cvt_pk_bf16(a.x, a.y); w.y = cvt_pk_bf16(b.x, b.y); w.z = cvt_pk_bf16(c.x, c.y); w.w = cvt_pk_bf16(d.x, d.y);
;                     *(u32x4*)(rowp + bj * HALF) = w; }
;                 if (isv) { s1 += __shfl_xor(s1, 16); s1 += __shfl_xor(s1, 32); s2 += __shfl_xor(s2, 16); s2 += __shfl_xor(s2, 32);
;                     if (fq == 0) { const int rl = ai * HALF + wr * 64 + m * 16 + fr; part[rl * 4 + wc] = s1; part[1024 + rl * 4 + wc] = s2; } } }
	s_nop 0
	v_pk_mul_f32 v[2:3], v[2:3], v[24:25]
	v_pk_mul_f32 v[24:25], v[8:9], v[8:9]
	v_pk_mul_f32 v[2:3], v[26:27], v[2:3]
	v_pk_mul_f32 v[24:25], v[24:25], s[76:77] op_sel_hi:[1,0]
	v_max_f32_e32 v26, 0, v6
	v_max_f32_e32 v27, 0, v7
	v_fma_f32 v0, -|v6|, v2, v26
	v_fma_f32 v2, -|v7|, v3, v27
	s_nop 0
	s_nop 0
	s_nop 0
	s_nop 0
	v_fma_f32 v6, |v8|, s64, 1.0
	v_fma_f32 v7, |v9|, s64, 1.0
	s_nop 0
	v_rcp_f32_e32 v6, v6
	v_rcp_f32_e32 v7, v7
	v_exp_f32_e32 v24, v24
	v_exp_f32_e32 v25, v25
	s_nop 0
	v_pk_fma_f32 v[26:27], v[6:7], s[66:67], v[10:11] op_sel_hi:[1,0,0]
	s_nop 0
	v_pk_fma_f32 v[26:27], v[6:7], v[26:27], s[70:71] op_sel_hi:[1,1,0]
	s_nop 0
	v_pk_fma_f32 v[26:27], v[6:7], v[26:27], s[72:73] op_sel_hi:[1,1,0]
	s_nop 0
	v_pk_fma_f32 v[26:27], v[6:7], v[26:27], s[74:75] op_sel_hi:[1,1,0]
	s_nop 0
	v_pk_mul_f32 v[6:7], v[6:7], v[26:27]
	v_pk_mul_f32 v[26:27], v[22:23], v[22:23]
	v_pk_mul_f32 v[6:7], v[24:25], v[6:7]
	v_pk_mul_f32 v[26:27], v[26:27], s[76:77] op_sel_hi:[1,0]
	v_max_f32_e32 v24, 0, v8
	v_max_f32_e32 v25, 0, v9
	v_fma_f32 v3, -|v8|, v6, v24
	v_fma_f32 v6, -|v9|, v7, v25
	s_nop 0
	s_nop 0
	s_nop 0
	s_nop 0
	v_fma_f32 v8, |v22|, s64, 1.0
	v_fma_f32 v9, |v23|, s64, 1.0
	s_nop 0
	v_rcp_f32_e32 v8, v8
	v_rcp_f32_e32 v9, v9
	v_exp_f32_e32 v26, v26
	v_exp_f32_e32 v27, v27
	s_nop 0
	v_pk_fma_f32 v[24:25], v[8:9], s[66:67], v[10:11] op_sel_hi:[1,0,0]
	s_nop 0
	v_pk_fma_f32 v[24:25], v[8:9], v[24:25], s[70:71] op_sel_hi:[1,1,0]
	s_nop 0
	v_pk_fma_f32 v[24:25], v[8:9], v[24:25], s[72:73] op_sel_hi:[1,1,0]
	s_nop 0
	v_pk_fma_f32 v[24:25], v[8:9], v[24:25], s[74:75] op_sel_hi:[1,1,0]
	s_nop 0
	v_pk_mul_f32 v[8:9], v[8:9], v[24:25]
	v_pk_mul_f32 v[24:25], v[4:5], v[4:5]
	v_pk_mul_f32 v[8:9], v[26:27], v[8:9]
	s_nop 0
	v_max_f32_e32 v26, 0, v22
	v_max_f32_e32 v27, 0, v23
	v_fma_f32 v7, -|v22|, v8, v26
	v_fma_f32 v8, -|v23|, v9, v27
	s_nop 0
	s_nop 0
	s_nop 0
	s_nop 0
	v_fma_f32 v22, |v4|, s64, 1.0
	v_fma_f32 v23, |v5|, s64, 1.0
	s_nop 0
	v_rcp_f32_e32 v22, v22
	v_rcp_f32_e32 v23, v23
	s_nop 0
	v_pk_fma_f32 v[10:11], v[22:23], s[66:67], v[10:11] op_sel_hi:[1,0,0]
	s_nop 0
	v_pk_fma_f32 v[10:11], v[22:23], v[10:11], s[70:71] op_sel_hi:[1,1,0]
	s_nop 0
	v_pk_fma_f32 v[10:11], v[22:23], v[10:11], s[72:73] op_sel_hi:[1,1,0]
	s_nop 0
	v_pk_fma_f32 v[10:11], v[22:23], v[10:11], s[74:75] op_sel_hi:[1,1,0]
	s_nop 0
	v_pk_mul_f32 v[10:11], v[22:23], v[10:11]
	v_pk_mul_f32 v[22:23], v[24:25], s[76:77] op_sel_hi:[1,0]
	s_nop 0
	v_exp_f32_e32 v22, v22
	v_exp_f32_e32 v23, v23
	s_nop 0
	v_pk_mul_f32 v[10:11], v[22:23], v[10:11]
	s_nop 0
	v_max_f32_e32 v22, 0, v4
	v_max_f32_e32 v23, 0, v5
	v_fma_f32 v4, -|v4|, v10, v22
	v_fma_f32 v5, -|v5|, v11, v23
	s_nop 0
	s_nop 0
	s_nop 0
	v_cvt_pk_bf16_f32 v22, v0, v2
	s_nop 1
	s_nop 0
	s_and_b64 vcc, exec, s[10:11]
	v_cvt_pk_bf16_f32 v23, v3, v6
	v_cvt_pk_bf16_f32 v24, v7, v8
	v_cvt_pk_bf16_f32 v25, v4, v5
	global_store_dwordx4 v[18:19], v[22:25], off offset:256
	s_cbranch_vccnz .LBB0_384
	v_mul_f32_e32 v9, v15, v15
	v_mul_f32_e32 v10, v17, v17
	v_fmac_f32_e32 v9, v14, v14
	v_fmac_f32_e32 v10, v16, v16
	v_add_f32_e32 v9, v9, v10
	v_mul_f32_e32 v10, v21, v21
	v_mul_f32_e32 v11, v13, v13
	v_fmac_f32_e32 v10, v20, v20
	v_fmac_f32_e32 v11, v12, v12
	v_add_f32_e32 v10, v10, v11
	v_add_f32_e32 v9, v9, v10
	v_mul_f32_e32 v10, v2, v2
	v_fmac_f32_e32 v10, v0, v0
	v_mul_f32_e32 v11, v6, v6
	v_add_f32_e32 v0, v0, v2
	v_add_f32_e32 v2, v3, v6
	v_fmac_f32_e32 v11, v3, v3
	v_add_f32_e32 v14, v14, v15
	v_add_f32_e32 v15, v16, v17
	v_add_f32_e32 v0, v0, v2
	v_add_f32_e32 v2, v7, v8
	v_add_f32_e32 v3, v4, v5
	v_add_f32_e32 v14, v14, v15
	v_add_f32_e32 v15, v20, v21
	v_add_f32_e32 v12, v12, v13
	v_add_f32_e32 v2, v2, v3
	v_and_b32_e32 v3, 64, v226
	v_add_f32_e32 v12, v15, v12
	v_add_f32_e32 v0, v0, v2
	v_xor_b32_e32 v2, 16, v226
	v_add_u32_e32 v3, 64, v3
	v_add_f32_e32 v12, v14, v12
	v_cmp_lt_i32_e32 vcc, v2, v3
	v_add_f32_e32 v10, v10, v11
	v_mul_f32_e32 v11, v8, v8
	v_mul_f32_e32 v18, v5, v5
	v_add_f32_e32 v12, 0, v12
	v_cndmask_b32_e32 v2, v226, v2, vcc
	v_fmac_f32_e32 v11, v7, v7
	v_add_f32_e32 v0, v0, v12
	v_lshlrev_b32_e32 v2, 2, v2
	v_fmac_f32_e32 v18, v4, v4
	v_mov_b32_e32 v5, v0
	s_nop 1
	v_permlane16_swap_b32_e32 v5, v0
	v_add_f32_e32 v4, v11, v18
	v_add_f32_e32 v4, v10, v4
	v_add_f32_e32 v4, v9, v4
	v_mov_b32_e32 v6, v4
	s_nop 1
	v_permlane16_swap_b32_e32 v6, v4
	s_waitcnt lgkmcnt(0)
	v_add_f32_e32 v0, v0, v5
	v_xor_b32_e32 v5, 32, v226
	v_cmp_lt_i32_e32 vcc, v5, v3
	v_add_f32_e32 v3, v4, v6
	s_nop 0
	v_cndmask_b32_e32 v2, v226, v5, vcc
	v_lshlrev_b32_e32 v5, 2, v2
	v_mov_b32_e32 v2, v0
	s_nop 1
	v_permlane32_swap_b32_e32 v2, v0
	v_mov_b32_e32 v4, v3
	s_nop 1
	v_permlane32_swap_b32_e32 v4, v3
	s_and_saveexec_b64 s[4:5], s[6:7]
	s_cbranch_execz .LBB0_383
	s_waitcnt lgkmcnt(0)
	v_add_f32_e32 v3, v3, v4
	v_add_f32_e32 v0, v0, v2
	ds_write2st64_b32 v186, v0, v3 offset0:11 offset1:27
